# GEMM K-loops: six-DMA load segments back to ds_read-first order, two-DMA segments keep DMA-first (to attribute the earlier reorder gain)
# speedup vs baseline: 1.0075x; 1.0050x over previous
.LBB0_94:
	s_add_u32 s24, s22, 0x4000
	s_addc_u32 s25, s23, 0
	s_cmp_eq_u32 s60, 60
	s_cselect_b32 s28, s2, s24
	s_cselect_b32 s29, s1, s25
	s_cselect_b32 s26, s15, s48
	s_cselect_b32 s27, s13, s49
	s_add_u32 s24, s28, 0x8000
	s_addc_u32 s25, s29, 0
	s_add_i32 m0, s21, 0xc000
	s_nop 0
	global_load_lds_dwordx4 v128, s[22:23]
	s_add_i32 m0, s21, 0xe000
	s_nop 0
	global_load_lds_dwordx4 v130, s[22:23]
	ds_read_b128 v[142:145], v160
	ds_read_b128 v[146:149], v160 offset:1024
	ds_read_b128 v[168:171], v160 offset:2048
	ds_read_b128 v[172:175], v160 offset:3072
	ds_read_b128 v[176:179], v161
	ds_read_b128 v[180:183], v161 offset:1024
	ds_read_b128 v[184:187], v161 offset:2048
	ds_read_b128 v[188:191], v161 offset:3072
	ds_read_b128 v[196:199], v162
	ds_read_b128 v[200:203], v162 offset:1024
	ds_read_b128 v[204:207], v162 offset:2048
	ds_read_b128 v[208:211], v162 offset:3072
	ds_read_b128 v[212:215], v162 offset:4096
	ds_read_b128 v[216:219], v162 offset:5120
	ds_read_b128 v[220:223], v162 offset:6144
	ds_read_b128 v[224:227], v162 offset:7168
	s_waitcnt vmcnt(8)
	s_waitcnt lgkmcnt(0)
	s_barrier
	s_setprio 1
	s_waitcnt lgkmcnt(0)
	v_mfma_f32_16x16x32_bf16 v[124:127], v[142:145], v[196:199], v[124:127]
	v_mfma_f32_16x16x32_bf16 v[120:123], v[168:171], v[196:199], v[120:123]
	v_mfma_f32_16x16x32_bf16 v[108:111], v[142:145], v[204:207], v[108:111]
	v_mfma_f32_16x16x32_bf16 v[104:107], v[168:171], v[204:207], v[104:107]
	v_mfma_f32_16x16x32_bf16 v[92:95], v[142:145], v[212:215], v[92:95]
	v_mfma_f32_16x16x32_bf16 v[88:91], v[168:171], v[212:215], v[88:91]
	v_mfma_f32_16x16x32_bf16 v[76:79], v[142:145], v[220:223], v[76:79]
	v_mfma_f32_16x16x32_bf16 v[72:75], v[168:171], v[220:223], v[72:75]
	v_mfma_f32_16x16x32_bf16 v[124:127], v[146:149], v[200:203], v[124:127]
	v_mfma_f32_16x16x32_bf16 v[120:123], v[172:175], v[200:203], v[120:123]
	v_mfma_f32_16x16x32_bf16 v[108:111], v[146:149], v[208:211], v[108:111]
	v_mfma_f32_16x16x32_bf16 v[104:107], v[172:175], v[208:211], v[104:107]
	v_mfma_f32_16x16x32_bf16 v[92:95], v[146:149], v[216:219], v[92:95]
	v_mfma_f32_16x16x32_bf16 v[88:91], v[172:175], v[216:219], v[88:91]
	v_mfma_f32_16x16x32_bf16 v[76:79], v[146:149], v[224:227], v[76:79]
	v_mfma_f32_16x16x32_bf16 v[72:75], v[172:175], v[224:227], v[72:75]
	s_setprio 0
	s_setprio 1
	v_mfma_f32_16x16x32_bf16 v[116:119], v[176:179], v[196:199], v[116:119]
	v_mfma_f32_16x16x32_bf16 v[112:115], v[184:187], v[196:199], v[112:115]
	v_mfma_f32_16x16x32_bf16 v[100:103], v[176:179], v[204:207], v[100:103]
	v_mfma_f32_16x16x32_bf16 v[96:99], v[184:187], v[204:207], v[96:99]
	v_mfma_f32_16x16x32_bf16 v[84:87], v[176:179], v[212:215], v[84:87]
	v_mfma_f32_16x16x32_bf16 v[80:83], v[184:187], v[212:215], v[80:83]
	v_mfma_f32_16x16x32_bf16 v[68:71], v[176:179], v[220:223], v[68:71]
	v_mfma_f32_16x16x32_bf16 v[64:67], v[184:187], v[220:223], v[64:67]
	v_mfma_f32_16x16x32_bf16 v[116:119], v[180:183], v[200:203], v[116:119]
	v_mfma_f32_16x16x32_bf16 v[112:115], v[188:191], v[200:203], v[112:115]
	v_mfma_f32_16x16x32_bf16 v[100:103], v[180:183], v[208:211], v[100:103]
	v_mfma_f32_16x16x32_bf16 v[96:99], v[188:191], v[208:211], v[96:99]
	v_mfma_f32_16x16x32_bf16 v[84:87], v[180:183], v[216:219], v[84:87]
	v_mfma_f32_16x16x32_bf16 v[80:83], v[188:191], v[216:219], v[80:83]
	v_mfma_f32_16x16x32_bf16 v[68:71], v[180:183], v[224:227], v[68:71]
	v_mfma_f32_16x16x32_bf16 v[64:67], v[188:191], v[224:227], v[64:67]
	s_setprio 0
	s_barrier
	s_add_i32 s61, s41, s3
	s_mov_b32 m0, s61
	s_nop 0
	ds_read_b128 v[196:199], v162 offset:16384
	ds_read_b128 v[200:203], v162 offset:17408
	ds_read_b128 v[204:207], v162 offset:18432
	ds_read_b128 v[208:211], v162 offset:19456
	ds_read_b128 v[212:215], v162 offset:20480
	ds_read_b128 v[216:219], v162 offset:21504
	ds_read_b128 v[220:223], v162 offset:22528
	ds_read_b128 v[224:227], v162 offset:23552
	global_load_lds_dwordx4 v128, s[26:27]
	s_add_i32 m0, s61, 0x2000
	s_add_u32 s62, s26, 0x4000
	s_addc_u32 s63, s27, 0
	s_add_i32 s61, s42, s3
	global_load_lds_dwordx4 v130, s[26:27]
	s_mov_b32 m0, s61
	s_nop 0
	global_load_lds_dwordx4 v128, s[62:63]
	s_add_i32 m0, s61, 0x2000
	s_nop 0
	global_load_lds_dwordx4 v130, s[62:63]
	s_mov_b32 m0, s21
	s_nop 0
	global_load_lds_dwordx4 v128, s[28:29]
	s_mov_b32 m0, s30
	s_nop 0
	global_load_lds_dwordx4 v130, s[28:29]
	s_waitcnt vmcnt(8)
	s_waitcnt lgkmcnt(0)
	s_barrier
	s_setprio 1
	s_waitcnt lgkmcnt(0)
	v_mfma_f32_16x16x32_bf16 v[60:63], v[142:145], v[196:199], v[60:63]
	v_mfma_f32_16x16x32_bf16 v[56:59], v[168:171], v[196:199], v[56:59]
	v_mfma_f32_16x16x32_bf16 v[44:47], v[142:145], v[204:207], v[44:47]
	v_mfma_f32_16x16x32_bf16 v[40:43], v[168:171], v[204:207], v[40:43]
	v_mfma_f32_16x16x32_bf16 v[28:31], v[142:145], v[212:215], v[28:31]
	v_mfma_f32_16x16x32_bf16 v[24:27], v[168:171], v[212:215], v[24:27]
	v_mfma_f32_16x16x32_bf16 v[12:15], v[142:145], v[220:223], v[12:15]
	v_mfma_f32_16x16x32_bf16 v[8:11], v[168:171], v[220:223], v[8:11]
	v_mfma_f32_16x16x32_bf16 v[60:63], v[146:149], v[200:203], v[60:63]
	v_mfma_f32_16x16x32_bf16 v[56:59], v[172:175], v[200:203], v[56:59]
	v_mfma_f32_16x16x32_bf16 v[44:47], v[146:149], v[208:211], v[44:47]
	v_mfma_f32_16x16x32_bf16 v[40:43], v[172:175], v[208:211], v[40:43]
	v_mfma_f32_16x16x32_bf16 v[28:31], v[146:149], v[216:219], v[28:31]
	v_mfma_f32_16x16x32_bf16 v[24:27], v[172:175], v[216:219], v[24:27]
	v_mfma_f32_16x16x32_bf16 v[12:15], v[146:149], v[224:227], v[12:15]
	v_mfma_f32_16x16x32_bf16 v[8:11], v[172:175], v[224:227], v[8:11]
	s_setprio 0
	s_setprio 1
	v_mfma_f32_16x16x32_bf16 v[52:55], v[176:179], v[196:199], v[52:55]
	v_mfma_f32_16x16x32_bf16 v[48:51], v[184:187], v[196:199], v[48:51]
	v_mfma_f32_16x16x32_bf16 v[36:39], v[176:179], v[204:207], v[36:39]
	v_mfma_f32_16x16x32_bf16 v[32:35], v[184:187], v[204:207], v[32:35]
	v_mfma_f32_16x16x32_bf16 v[20:23], v[176:179], v[212:215], v[20:23]
	v_mfma_f32_16x16x32_bf16 v[16:19], v[184:187], v[212:215], v[16:19]
	v_mfma_f32_16x16x32_bf16 v[4:7], v[176:179], v[220:223], v[4:7]
	v_mfma_f32_16x16x32_bf16 v[0:3], v[184:187], v[220:223], v[0:3]
	v_mfma_f32_16x16x32_bf16 v[52:55], v[180:183], v[200:203], v[52:55]
	v_mfma_f32_16x16x32_bf16 v[48:51], v[188:191], v[200:203], v[48:51]
	v_mfma_f32_16x16x32_bf16 v[36:39], v[180:183], v[208:211], v[36:39]
	v_mfma_f32_16x16x32_bf16 v[32:35], v[188:191], v[208:211], v[32:35]
	v_mfma_f32_16x16x32_bf16 v[20:23], v[180:183], v[216:219], v[20:23]
	v_mfma_f32_16x16x32_bf16 v[16:19], v[188:191], v[216:219], v[16:19]
	v_mfma_f32_16x16x32_bf16 v[4:7], v[180:183], v[224:227], v[4:7]
	v_mfma_f32_16x16x32_bf16 v[0:3], v[188:191], v[224:227], v[0:3]
	s_setprio 0
	s_barrier
	s_add_i32 s61, 0, 0x18000
	v_add_u32_e32 v132, s61, v135
	s_add_i32 s62, 0, 0x1c000
	s_add_u32 s28, s28, 0x4000
	s_addc_u32 s29, s29, 0
	s_mov_b32 m0, s31
	s_nop 0
	global_load_lds_dwordx4 v128, s[28:29]
	s_mov_b32 m0, s33
	s_nop 0
	global_load_lds_dwordx4 v130, s[28:29]
	ds_read_b128 v[142:145], v132
	ds_read_b128 v[146:149], v132 offset:1024
	ds_read_b128 v[168:171], v132 offset:2048
	ds_read_b128 v[172:175], v132 offset:3072
	v_add_u32_e32 v132, s62, v135
	ds_read_b128 v[176:179], v132
	ds_read_b128 v[180:183], v132 offset:1024
	ds_read_b128 v[184:187], v132 offset:2048
	ds_read_b128 v[188:191], v132 offset:3072
	ds_read_b128 v[196:199], v162 offset:32768
	ds_read_b128 v[200:203], v162 offset:33792
	ds_read_b128 v[204:207], v162 offset:34816
	ds_read_b128 v[208:211], v162 offset:35840
	ds_read_b128 v[212:215], v162 offset:36864
	ds_read_b128 v[216:219], v162 offset:37888
	ds_read_b128 v[220:223], v162 offset:38912
	ds_read_b128 v[224:227], v162 offset:39936
	s_waitcnt vmcnt(8)
	s_waitcnt lgkmcnt(0)
	s_barrier
	s_setprio 1
	s_waitcnt lgkmcnt(0)
	v_mfma_f32_16x16x32_bf16 v[124:127], v[142:145], v[196:199], v[124:127]
	v_mfma_f32_16x16x32_bf16 v[120:123], v[168:171], v[196:199], v[120:123]
	v_mfma_f32_16x16x32_bf16 v[108:111], v[142:145], v[204:207], v[108:111]
	v_mfma_f32_16x16x32_bf16 v[104:107], v[168:171], v[204:207], v[104:107]
	v_mfma_f32_16x16x32_bf16 v[92:95], v[142:145], v[212:215], v[92:95]
	v_mfma_f32_16x16x32_bf16 v[88:91], v[168:171], v[212:215], v[88:91]
	v_mfma_f32_16x16x32_bf16 v[76:79], v[142:145], v[220:223], v[76:79]
	v_mfma_f32_16x16x32_bf16 v[72:75], v[168:171], v[220:223], v[72:75]
	v_mfma_f32_16x16x32_bf16 v[124:127], v[146:149], v[200:203], v[124:127]
	v_mfma_f32_16x16x32_bf16 v[120:123], v[172:175], v[200:203], v[120:123]
	v_mfma_f32_16x16x32_bf16 v[108:111], v[146:149], v[208:211], v[108:111]
	v_mfma_f32_16x16x32_bf16 v[104:107], v[172:175], v[208:211], v[104:107]
	v_mfma_f32_16x16x32_bf16 v[92:95], v[146:149], v[216:219], v[92:95]
	v_mfma_f32_16x16x32_bf16 v[88:91], v[172:175], v[216:219], v[88:91]
	v_mfma_f32_16x16x32_bf16 v[76:79], v[146:149], v[224:227], v[76:79]
	v_mfma_f32_16x16x32_bf16 v[72:75], v[172:175], v[224:227], v[72:75]
	s_setprio 0
	s_setprio 1
	v_mfma_f32_16x16x32_bf16 v[116:119], v[176:179], v[196:199], v[116:119]
	v_mfma_f32_16x16x32_bf16 v[112:115], v[184:187], v[196:199], v[112:115]
	v_mfma_f32_16x16x32_bf16 v[100:103], v[176:179], v[204:207], v[100:103]
	v_mfma_f32_16x16x32_bf16 v[96:99], v[184:187], v[204:207], v[96:99]
	v_mfma_f32_16x16x32_bf16 v[84:87], v[176:179], v[212:215], v[84:87]
	v_mfma_f32_16x16x32_bf16 v[80:83], v[184:187], v[212:215], v[80:83]
	v_mfma_f32_16x16x32_bf16 v[68:71], v[176:179], v[220:223], v[68:71]
	v_mfma_f32_16x16x32_bf16 v[64:67], v[184:187], v[220:223], v[64:67]
	v_mfma_f32_16x16x32_bf16 v[116:119], v[180:183], v[200:203], v[116:119]
	v_mfma_f32_16x16x32_bf16 v[112:115], v[188:191], v[200:203], v[112:115]
	v_mfma_f32_16x16x32_bf16 v[100:103], v[180:183], v[208:211], v[100:103]
	v_mfma_f32_16x16x32_bf16 v[96:99], v[188:191], v[208:211], v[96:99]
	v_mfma_f32_16x16x32_bf16 v[84:87], v[180:183], v[216:219], v[84:87]
	v_mfma_f32_16x16x32_bf16 v[80:83], v[188:191], v[216:219], v[80:83]
	v_mfma_f32_16x16x32_bf16 v[68:71], v[180:183], v[224:227], v[68:71]
	v_mfma_f32_16x16x32_bf16 v[64:67], v[188:191], v[224:227], v[64:67]
	s_setprio 0
	s_barrier
	s_add_u32 s28, s26, 0x8000
	s_addc_u32 s29, s27, 0
	s_add_i32 s61, s61, s3
	s_mov_b32 m0, s61
	s_nop 0
	ds_read_b128 v[196:199], v162 offset:49152
	ds_read_b128 v[200:203], v162 offset:50176
	ds_read_b128 v[204:207], v162 offset:51200
	ds_read_b128 v[208:211], v162 offset:52224
	ds_read_b128 v[212:215], v162 offset:53248
	ds_read_b128 v[216:219], v162 offset:54272
	ds_read_b128 v[220:223], v162 offset:55296
	ds_read_b128 v[224:227], v162 offset:56320
	global_load_lds_dwordx4 v128, s[28:29]
	s_add_i32 m0, s61, 0x2000
	s_add_u32 s26, s26, 0xc000
	s_addc_u32 s27, s27, 0
	global_load_lds_dwordx4 v130, s[28:29]
	s_add_i32 s28, s62, s3
	s_mov_b32 m0, s28
	s_nop 0
	global_load_lds_dwordx4 v128, s[26:27]
	s_add_i32 m0, s28, 0x2000
	s_nop 0
	global_load_lds_dwordx4 v130, s[26:27]
	s_mov_b32 m0, s37
	s_nop 0
	global_load_lds_dwordx4 v128, s[24:25]
	s_mov_b32 m0, s38
	s_nop 0
	global_load_lds_dwordx4 v130, s[24:25]
	s_waitcnt vmcnt(8)
	s_waitcnt lgkmcnt(0)
	s_barrier
	s_setprio 1
	s_waitcnt lgkmcnt(0)
	v_mfma_f32_16x16x32_bf16 v[60:63], v[142:145], v[196:199], v[60:63]
	v_mfma_f32_16x16x32_bf16 v[56:59], v[168:171], v[196:199], v[56:59]
	v_mfma_f32_16x16x32_bf16 v[44:47], v[142:145], v[204:207], v[44:47]
	v_mfma_f32_16x16x32_bf16 v[40:43], v[168:171], v[204:207], v[40:43]
	v_mfma_f32_16x16x32_bf16 v[28:31], v[142:145], v[212:215], v[28:31]
	v_mfma_f32_16x16x32_bf16 v[24:27], v[168:171], v[212:215], v[24:27]
	v_mfma_f32_16x16x32_bf16 v[12:15], v[142:145], v[220:223], v[12:15]
	v_mfma_f32_16x16x32_bf16 v[8:11], v[168:171], v[220:223], v[8:11]
	v_mfma_f32_16x16x32_bf16 v[60:63], v[146:149], v[200:203], v[60:63]
	v_mfma_f32_16x16x32_bf16 v[56:59], v[172:175], v[200:203], v[56:59]
	v_mfma_f32_16x16x32_bf16 v[44:47], v[146:149], v[208:211], v[44:47]
	v_mfma_f32_16x16x32_bf16 v[40:43], v[172:175], v[208:211], v[40:43]
	v_mfma_f32_16x16x32_bf16 v[28:31], v[146:149], v[216:219], v[28:31]
	v_mfma_f32_16x16x32_bf16 v[24:27], v[172:175], v[216:219], v[24:27]
	v_mfma_f32_16x16x32_bf16 v[12:15], v[146:149], v[224:227], v[12:15]
	v_mfma_f32_16x16x32_bf16 v[8:11], v[172:175], v[224:227], v[8:11]
	s_setprio 0
	s_setprio 1
	v_mfma_f32_16x16x32_bf16 v[52:55], v[176:179], v[196:199], v[52:55]
	v_mfma_f32_16x16x32_bf16 v[48:51], v[184:187], v[196:199], v[48:51]
	v_mfma_f32_16x16x32_bf16 v[36:39], v[176:179], v[204:207], v[36:39]
	v_mfma_f32_16x16x32_bf16 v[32:35], v[184:187], v[204:207], v[32:35]
	v_mfma_f32_16x16x32_bf16 v[20:23], v[176:179], v[212:215], v[20:23]
	v_mfma_f32_16x16x32_bf16 v[16:19], v[184:187], v[212:215], v[16:19]
	v_mfma_f32_16x16x32_bf16 v[4:7], v[176:179], v[220:223], v[4:7]
	v_mfma_f32_16x16x32_bf16 v[0:3], v[184:187], v[220:223], v[0:3]
	v_mfma_f32_16x16x32_bf16 v[52:55], v[180:183], v[200:203], v[52:55]
	v_mfma_f32_16x16x32_bf16 v[48:51], v[188:191], v[200:203], v[48:51]
	v_mfma_f32_16x16x32_bf16 v[36:39], v[180:183], v[208:211], v[36:39]
	v_mfma_f32_16x16x32_bf16 v[32:35], v[188:191], v[208:211], v[32:35]
	v_mfma_f32_16x16x32_bf16 v[20:23], v[180:183], v[216:219], v[20:23]
	v_mfma_f32_16x16x32_bf16 v[16:19], v[188:191], v[216:219], v[16:19]
	v_mfma_f32_16x16x32_bf16 v[4:7], v[180:183], v[224:227], v[4:7]
	v_mfma_f32_16x16x32_bf16 v[0:3], v[188:191], v[224:227], v[0:3]
	s_setprio 0
	s_barrier
	s_add_i32 s60, s60, 2
	s_add_u32 s22, s22, 0x10000
	s_addc_u32 s23, s23, 0
	s_add_u32 s48, s48, 0x10000
	s_addc_u32 s49, s49, 0
	s_cmp_gt_u32 s60, 61
	s_cbranch_scc0 .LBB0_94
	s_and_b64 vcc, exec, s[10:11]
	s_cbranch_vccz .LBB0_97
	s_barrier

.LBB0_373:
	s_add_u32 s30, s28, 0x4000
	s_addc_u32 s31, s29, 0
	s_cmp_eq_u32 s49, 60
	s_cselect_b32 s36, s13, s30
	s_cselect_b32 s37, s2, s31
	s_cselect_b32 s34, s21, s27
	s_cselect_b32 s35, s19, s48
	s_add_u32 s30, s36, 0x8000
	s_addc_u32 s31, s37, 0
	s_add_i32 m0, s33, 0xc000
	s_nop 0
	global_load_lds_dwordx4 v144, s[28:29]
	s_add_i32 m0, s33, 0xe000
	s_nop 0
	global_load_lds_dwordx4 v146, s[28:29]
	ds_read_b128 v[128:131], v164
	ds_read_b128 v[132:135], v164 offset:1024
	ds_read_b128 v[136:139], v164 offset:2048
	ds_read_b128 v[140:143], v164 offset:3072
	ds_read_b128 v[154:157], v166
	ds_read_b128 v[170:173], v166 offset:1024
	ds_read_b128 v[174:177], v166 offset:2048
	ds_read_b128 v[178:181], v166 offset:3072
	ds_read_b128 v[182:185], v168
	ds_read_b128 v[186:189], v168 offset:1024
	ds_read_b128 v[190:193], v168 offset:2048
	ds_read_b128 v[196:199], v168 offset:3072
	ds_read_b128 v[200:203], v168 offset:4096
	ds_read_b128 v[204:207], v168 offset:5120
	ds_read_b128 v[208:211], v168 offset:6144
	ds_read_b128 v[212:215], v168 offset:7168
	s_waitcnt vmcnt(8)
	s_waitcnt lgkmcnt(0)
	s_barrier
	s_setprio 1
	s_waitcnt lgkmcnt(0)
	v_mfma_f32_16x16x32_bf16 v[124:127], v[128:131], v[182:185], v[124:127]
	v_mfma_f32_16x16x32_bf16 v[120:123], v[136:139], v[182:185], v[120:123]
	v_mfma_f32_16x16x32_bf16 v[108:111], v[128:131], v[190:193], v[108:111]
	v_mfma_f32_16x16x32_bf16 v[104:107], v[136:139], v[190:193], v[104:107]
	v_mfma_f32_16x16x32_bf16 v[92:95], v[128:131], v[200:203], v[92:95]
	v_mfma_f32_16x16x32_bf16 v[88:91], v[136:139], v[200:203], v[88:91]
	v_mfma_f32_16x16x32_bf16 v[76:79], v[128:131], v[208:211], v[76:79]
	v_mfma_f32_16x16x32_bf16 v[72:75], v[136:139], v[208:211], v[72:75]
	v_mfma_f32_16x16x32_bf16 v[124:127], v[132:135], v[186:189], v[124:127]
	v_mfma_f32_16x16x32_bf16 v[120:123], v[140:143], v[186:189], v[120:123]
	v_mfma_f32_16x16x32_bf16 v[108:111], v[132:135], v[196:199], v[108:111]
	v_mfma_f32_16x16x32_bf16 v[104:107], v[140:143], v[196:199], v[104:107]
	v_mfma_f32_16x16x32_bf16 v[92:95], v[132:135], v[204:207], v[92:95]
	v_mfma_f32_16x16x32_bf16 v[88:91], v[140:143], v[204:207], v[88:91]
	v_mfma_f32_16x16x32_bf16 v[76:79], v[132:135], v[212:215], v[76:79]
	v_mfma_f32_16x16x32_bf16 v[72:75], v[140:143], v[212:215], v[72:75]
	s_setprio 0
	s_setprio 1
	v_mfma_f32_16x16x32_bf16 v[116:119], v[154:157], v[182:185], v[116:119]
	v_mfma_f32_16x16x32_bf16 v[112:115], v[174:177], v[182:185], v[112:115]
	v_mfma_f32_16x16x32_bf16 v[100:103], v[154:157], v[190:193], v[100:103]
	v_mfma_f32_16x16x32_bf16 v[96:99], v[174:177], v[190:193], v[96:99]
	v_mfma_f32_16x16x32_bf16 v[84:87], v[154:157], v[200:203], v[84:87]
	v_mfma_f32_16x16x32_bf16 v[80:83], v[174:177], v[200:203], v[80:83]
	v_mfma_f32_16x16x32_bf16 v[68:71], v[154:157], v[208:211], v[68:71]
	v_mfma_f32_16x16x32_bf16 v[64:67], v[174:177], v[208:211], v[64:67]
	v_mfma_f32_16x16x32_bf16 v[116:119], v[170:173], v[186:189], v[116:119]
	v_mfma_f32_16x16x32_bf16 v[112:115], v[178:181], v[186:189], v[112:115]
	v_mfma_f32_16x16x32_bf16 v[100:103], v[170:173], v[196:199], v[100:103]
	v_mfma_f32_16x16x32_bf16 v[96:99], v[178:181], v[196:199], v[96:99]
	v_mfma_f32_16x16x32_bf16 v[84:87], v[170:173], v[204:207], v[84:87]
	v_mfma_f32_16x16x32_bf16 v[80:83], v[178:181], v[204:207], v[80:83]
	v_mfma_f32_16x16x32_bf16 v[68:71], v[170:173], v[212:215], v[68:71]
	v_mfma_f32_16x16x32_bf16 v[64:67], v[178:181], v[212:215], v[64:67]
	s_setprio 0
	s_barrier
	s_add_i32 s61, s57, s3
	s_mov_b32 m0, s61
	s_nop 0
	ds_read_b128 v[182:185], v168 offset:16384
	ds_read_b128 v[186:189], v168 offset:17408
	ds_read_b128 v[190:193], v168 offset:18432
	ds_read_b128 v[196:199], v168 offset:19456
	ds_read_b128 v[200:203], v168 offset:20480
	ds_read_b128 v[204:207], v168 offset:21504
	ds_read_b128 v[208:211], v168 offset:22528
	ds_read_b128 v[212:215], v168 offset:23552
	global_load_lds_dwordx4 v144, s[34:35]
	s_add_i32 m0, s61, 0x2000
	s_add_u32 s62, s34, 0x4000
	s_addc_u32 s63, s35, 0
	s_add_i32 s61, s60, s3
	global_load_lds_dwordx4 v146, s[34:35]
	s_mov_b32 m0, s61
	s_nop 0
	global_load_lds_dwordx4 v144, s[62:63]
	s_add_i32 m0, s61, 0x2000
	s_nop 0
	global_load_lds_dwordx4 v146, s[62:63]
	s_mov_b32 m0, s33
	s_nop 0
	global_load_lds_dwordx4 v144, s[36:37]
	s_mov_b32 m0, s38
	s_nop 0
	global_load_lds_dwordx4 v146, s[36:37]
	s_waitcnt vmcnt(8)
	s_waitcnt lgkmcnt(0)
	s_barrier
	s_setprio 1
	s_waitcnt lgkmcnt(0)
	v_mfma_f32_16x16x32_bf16 v[60:63], v[128:131], v[182:185], v[60:63]
	v_mfma_f32_16x16x32_bf16 v[56:59], v[136:139], v[182:185], v[56:59]
	v_mfma_f32_16x16x32_bf16 v[44:47], v[128:131], v[190:193], v[44:47]
	v_mfma_f32_16x16x32_bf16 v[40:43], v[136:139], v[190:193], v[40:43]
	v_mfma_f32_16x16x32_bf16 v[28:31], v[128:131], v[200:203], v[28:31]
	v_mfma_f32_16x16x32_bf16 v[24:27], v[136:139], v[200:203], v[24:27]
	v_mfma_f32_16x16x32_bf16 v[12:15], v[128:131], v[208:211], v[12:15]
	v_mfma_f32_16x16x32_bf16 v[8:11], v[136:139], v[208:211], v[8:11]
	v_mfma_f32_16x16x32_bf16 v[60:63], v[132:135], v[186:189], v[60:63]
	v_mfma_f32_16x16x32_bf16 v[56:59], v[140:143], v[186:189], v[56:59]
	v_mfma_f32_16x16x32_bf16 v[44:47], v[132:135], v[196:199], v[44:47]
	v_mfma_f32_16x16x32_bf16 v[40:43], v[140:143], v[196:199], v[40:43]
	v_mfma_f32_16x16x32_bf16 v[28:31], v[132:135], v[204:207], v[28:31]
	v_mfma_f32_16x16x32_bf16 v[24:27], v[140:143], v[204:207], v[24:27]
	v_mfma_f32_16x16x32_bf16 v[12:15], v[132:135], v[212:215], v[12:15]
	v_mfma_f32_16x16x32_bf16 v[8:11], v[140:143], v[212:215], v[8:11]
	s_setprio 0
	s_setprio 1
	v_mfma_f32_16x16x32_bf16 v[52:55], v[154:157], v[182:185], v[52:55]
	v_mfma_f32_16x16x32_bf16 v[48:51], v[174:177], v[182:185], v[48:51]
	v_mfma_f32_16x16x32_bf16 v[36:39], v[154:157], v[190:193], v[36:39]
	v_mfma_f32_16x16x32_bf16 v[32:35], v[174:177], v[190:193], v[32:35]
	v_mfma_f32_16x16x32_bf16 v[20:23], v[154:157], v[200:203], v[20:23]
	v_mfma_f32_16x16x32_bf16 v[16:19], v[174:177], v[200:203], v[16:19]
	v_mfma_f32_16x16x32_bf16 v[4:7], v[154:157], v[208:211], v[4:7]
	v_mfma_f32_16x16x32_bf16 v[0:3], v[174:177], v[208:211], v[0:3]
	v_mfma_f32_16x16x32_bf16 v[52:55], v[170:173], v[186:189], v[52:55]
	v_mfma_f32_16x16x32_bf16 v[48:51], v[178:181], v[186:189], v[48:51]
	v_mfma_f32_16x16x32_bf16 v[36:39], v[170:173], v[196:199], v[36:39]
	v_mfma_f32_16x16x32_bf16 v[32:35], v[178:181], v[196:199], v[32:35]
	v_mfma_f32_16x16x32_bf16 v[20:23], v[170:173], v[204:207], v[20:23]
	v_mfma_f32_16x16x32_bf16 v[16:19], v[178:181], v[204:207], v[16:19]
	v_mfma_f32_16x16x32_bf16 v[4:7], v[170:173], v[212:215], v[4:7]
	v_mfma_f32_16x16x32_bf16 v[0:3], v[178:181], v[212:215], v[0:3]
	s_setprio 0
	s_barrier
	s_add_i32 s61, 0, 0x18000
	s_add_i32 s62, 0, 0x1c000
	v_add_u32_e32 v140, s61, v162
	v_add_u32_e32 v148, s62, v162
	s_add_u32 s36, s36, 0x4000
	s_addc_u32 s37, s37, 0
	s_mov_b32 m0, s39
	s_nop 0
	global_load_lds_dwordx4 v144, s[36:37]
	s_mov_b32 m0, s40
	s_nop 0
	global_load_lds_dwordx4 v146, s[36:37]
	ds_read_b128 v[128:131], v140
	ds_read_b128 v[132:135], v140 offset:1024
	ds_read_b128 v[136:139], v140 offset:2048
	ds_read_b128 v[140:143], v140 offset:3072
	ds_read_b128 v[154:157], v148
	ds_read_b128 v[170:173], v148 offset:1024
	ds_read_b128 v[174:177], v148 offset:2048
	ds_read_b128 v[178:181], v148 offset:3072
	ds_read_b128 v[182:185], v168 offset:32768
	ds_read_b128 v[186:189], v168 offset:33792
	ds_read_b128 v[190:193], v168 offset:34816
	ds_read_b128 v[196:199], v168 offset:35840
	ds_read_b128 v[200:203], v168 offset:36864
	ds_read_b128 v[204:207], v168 offset:37888
	ds_read_b128 v[208:211], v168 offset:38912
	ds_read_b128 v[212:215], v168 offset:39936
	s_waitcnt vmcnt(8)
	s_waitcnt lgkmcnt(0)
	s_barrier
	s_setprio 1
	s_waitcnt lgkmcnt(0)
	v_mfma_f32_16x16x32_bf16 v[124:127], v[128:131], v[182:185], v[124:127]
	v_mfma_f32_16x16x32_bf16 v[120:123], v[136:139], v[182:185], v[120:123]
	v_mfma_f32_16x16x32_bf16 v[108:111], v[128:131], v[190:193], v[108:111]
	v_mfma_f32_16x16x32_bf16 v[104:107], v[136:139], v[190:193], v[104:107]
	v_mfma_f32_16x16x32_bf16 v[92:95], v[128:131], v[200:203], v[92:95]
	v_mfma_f32_16x16x32_bf16 v[88:91], v[136:139], v[200:203], v[88:91]
	v_mfma_f32_16x16x32_bf16 v[76:79], v[128:131], v[208:211], v[76:79]
	v_mfma_f32_16x16x32_bf16 v[72:75], v[136:139], v[208:211], v[72:75]
	v_mfma_f32_16x16x32_bf16 v[124:127], v[132:135], v[186:189], v[124:127]
	v_mfma_f32_16x16x32_bf16 v[120:123], v[140:143], v[186:189], v[120:123]
	v_mfma_f32_16x16x32_bf16 v[108:111], v[132:135], v[196:199], v[108:111]
	v_mfma_f32_16x16x32_bf16 v[104:107], v[140:143], v[196:199], v[104:107]
	v_mfma_f32_16x16x32_bf16 v[92:95], v[132:135], v[204:207], v[92:95]
	v_mfma_f32_16x16x32_bf16 v[88:91], v[140:143], v[204:207], v[88:91]
	v_mfma_f32_16x16x32_bf16 v[76:79], v[132:135], v[212:215], v[76:79]
	v_mfma_f32_16x16x32_bf16 v[72:75], v[140:143], v[212:215], v[72:75]
	s_setprio 0
	s_setprio 1
	v_mfma_f32_16x16x32_bf16 v[116:119], v[154:157], v[182:185], v[116:119]
	v_mfma_f32_16x16x32_bf16 v[112:115], v[174:177], v[182:185], v[112:115]
	v_mfma_f32_16x16x32_bf16 v[100:103], v[154:157], v[190:193], v[100:103]
	v_mfma_f32_16x16x32_bf16 v[96:99], v[174:177], v[190:193], v[96:99]
	v_mfma_f32_16x16x32_bf16 v[84:87], v[154:157], v[200:203], v[84:87]
	v_mfma_f32_16x16x32_bf16 v[80:83], v[174:177], v[200:203], v[80:83]
	v_mfma_f32_16x16x32_bf16 v[68:71], v[154:157], v[208:211], v[68:71]
	v_mfma_f32_16x16x32_bf16 v[64:67], v[174:177], v[208:211], v[64:67]
	v_mfma_f32_16x16x32_bf16 v[116:119], v[170:173], v[186:189], v[116:119]
	v_mfma_f32_16x16x32_bf16 v[112:115], v[178:181], v[186:189], v[112:115]
	v_mfma_f32_16x16x32_bf16 v[100:103], v[170:173], v[196:199], v[100:103]
	v_mfma_f32_16x16x32_bf16 v[96:99], v[178:181], v[196:199], v[96:99]
	v_mfma_f32_16x16x32_bf16 v[84:87], v[170:173], v[204:207], v[84:87]
	v_mfma_f32_16x16x32_bf16 v[80:83], v[178:181], v[204:207], v[80:83]
	v_mfma_f32_16x16x32_bf16 v[68:71], v[170:173], v[212:215], v[68:71]
	v_mfma_f32_16x16x32_bf16 v[64:67], v[178:181], v[212:215], v[64:67]
	s_setprio 0
	s_barrier
	s_add_u32 s36, s34, 0x8000
	s_addc_u32 s37, s35, 0
	s_add_i32 s61, s61, s3
	s_mov_b32 m0, s61
	s_nop 0
	ds_read_b128 v[182:185], v168 offset:49152
	ds_read_b128 v[186:189], v168 offset:50176
	ds_read_b128 v[190:193], v168 offset:51200
	ds_read_b128 v[196:199], v168 offset:52224
	ds_read_b128 v[200:203], v168 offset:53248
	ds_read_b128 v[204:207], v168 offset:54272
	ds_read_b128 v[208:211], v168 offset:55296
	ds_read_b128 v[212:215], v168 offset:56320
	global_load_lds_dwordx4 v144, s[36:37]
	s_add_i32 m0, s61, 0x2000
	s_add_u32 s34, s34, 0xc000
	s_addc_u32 s35, s35, 0
	global_load_lds_dwordx4 v146, s[36:37]
	s_add_i32 s36, s62, s3
	s_mov_b32 m0, s36
	s_nop 0
	global_load_lds_dwordx4 v144, s[34:35]
	s_add_i32 m0, s36, 0x2000
	s_nop 0
	global_load_lds_dwordx4 v146, s[34:35]
	s_mov_b32 m0, s46
	s_nop 0
	global_load_lds_dwordx4 v144, s[30:31]
	s_mov_b32 m0, s47
	s_nop 0
	global_load_lds_dwordx4 v146, s[30:31]
	s_waitcnt vmcnt(8)
	s_waitcnt lgkmcnt(0)
	s_barrier
	s_setprio 1
	s_waitcnt lgkmcnt(0)
	v_mfma_f32_16x16x32_bf16 v[60:63], v[128:131], v[182:185], v[60:63]
	v_mfma_f32_16x16x32_bf16 v[56:59], v[136:139], v[182:185], v[56:59]
	v_mfma_f32_16x16x32_bf16 v[44:47], v[128:131], v[190:193], v[44:47]
	v_mfma_f32_16x16x32_bf16 v[40:43], v[136:139], v[190:193], v[40:43]
	v_mfma_f32_16x16x32_bf16 v[28:31], v[128:131], v[200:203], v[28:31]
	v_mfma_f32_16x16x32_bf16 v[24:27], v[136:139], v[200:203], v[24:27]
	v_mfma_f32_16x16x32_bf16 v[12:15], v[128:131], v[208:211], v[12:15]
	v_mfma_f32_16x16x32_bf16 v[8:11], v[136:139], v[208:211], v[8:11]
	v_mfma_f32_16x16x32_bf16 v[60:63], v[132:135], v[186:189], v[60:63]
	v_mfma_f32_16x16x32_bf16 v[56:59], v[140:143], v[186:189], v[56:59]
	v_mfma_f32_16x16x32_bf16 v[44:47], v[132:135], v[196:199], v[44:47]
	v_mfma_f32_16x16x32_bf16 v[40:43], v[140:143], v[196:199], v[40:43]
	v_mfma_f32_16x16x32_bf16 v[28:31], v[132:135], v[204:207], v[28:31]
	v_mfma_f32_16x16x32_bf16 v[24:27], v[140:143], v[204:207], v[24:27]
	v_mfma_f32_16x16x32_bf16 v[12:15], v[132:135], v[212:215], v[12:15]
	v_mfma_f32_16x16x32_bf16 v[8:11], v[140:143], v[212:215], v[8:11]
	s_setprio 0
	s_setprio 1
	v_mfma_f32_16x16x32_bf16 v[52:55], v[154:157], v[182:185], v[52:55]
	v_mfma_f32_16x16x32_bf16 v[48:51], v[174:177], v[182:185], v[48:51]
	v_mfma_f32_16x16x32_bf16 v[36:39], v[154:157], v[190:193], v[36:39]
	v_mfma_f32_16x16x32_bf16 v[32:35], v[174:177], v[190:193], v[32:35]
	v_mfma_f32_16x16x32_bf16 v[20:23], v[154:157], v[200:203], v[20:23]
	v_mfma_f32_16x16x32_bf16 v[16:19], v[174:177], v[200:203], v[16:19]
	v_mfma_f32_16x16x32_bf16 v[4:7], v[154:157], v[208:211], v[4:7]
	v_mfma_f32_16x16x32_bf16 v[0:3], v[174:177], v[208:211], v[0:3]
	v_mfma_f32_16x16x32_bf16 v[52:55], v[170:173], v[186:189], v[52:55]
	v_mfma_f32_16x16x32_bf16 v[48:51], v[178:181], v[186:189], v[48:51]
	v_mfma_f32_16x16x32_bf16 v[36:39], v[170:173], v[196:199], v[36:39]
	v_mfma_f32_16x16x32_bf16 v[32:35], v[178:181], v[196:199], v[32:35]
	v_mfma_f32_16x16x32_bf16 v[20:23], v[170:173], v[204:207], v[20:23]
	v_mfma_f32_16x16x32_bf16 v[16:19], v[178:181], v[204:207], v[16:19]
	v_mfma_f32_16x16x32_bf16 v[4:7], v[170:173], v[212:215], v[4:7]
	v_mfma_f32_16x16x32_bf16 v[0:3], v[178:181], v[212:215], v[0:3]
	s_setprio 0
	s_barrier
	s_add_i32 s49, s49, 2
	s_add_u32 s28, s28, 0x10000
	s_addc_u32 s29, s29, 0
	s_add_u32 s27, s27, 0x10000
	s_addc_u32 s48, s48, 0
	s_cmp_gt_u32 s49, 61
	s_cbranch_scc0 .LBB0_373
	s_and_b64 vcc, exec, s[16:17]
	s_cbranch_vccz .LBB0_376
	s_barrier

.LBB0_469:
	s_add_u32 s28, s26, 0x4000
	s_addc_u32 s29, s27, 0
	s_cmp_eq_u32 s49, 60
	s_cselect_b32 s34, s2, s28
	s_cselect_b32 s35, s1, s29
	s_cselect_b32 s30, s19, s25
	s_cselect_b32 s31, s17, s48
	s_add_u32 s28, s34, 0x8000
	s_addc_u32 s29, s35, 0
	s_add_i32 m0, s33, 0xc000
	s_nop 0
	global_load_lds_dwordx4 v176, s[26:27]
	s_add_i32 m0, s33, 0xe000
	s_nop 0
	global_load_lds_dwordx4 v178, s[26:27]
	ds_read_b128 v[128:131], v197
	ds_read_b128 v[132:135], v197 offset:1024
	ds_read_b128 v[136:139], v197 offset:2048
	ds_read_b128 v[140:143], v197 offset:3072
	ds_read_b128 v[144:147], v198
	ds_read_b128 v[148:151], v198 offset:1024
	ds_read_b128 v[152:155], v198 offset:2048
	ds_read_b128 v[156:159], v198 offset:3072
	ds_read_b128 v[160:163], v199
	ds_read_b128 v[164:167], v199 offset:1024
	ds_read_b128 v[168:171], v199 offset:2048
	ds_read_b128 v[172:175], v199 offset:3072
	ds_read_b128 v[188:191], v199 offset:4096
	ds_read_b128 v[202:205], v199 offset:5120
	ds_read_b128 v[206:209], v199 offset:6144
	ds_read_b128 v[210:213], v199 offset:7168
	s_waitcnt vmcnt(8)
	s_waitcnt lgkmcnt(0)
	s_barrier
	s_setprio 1
	s_waitcnt lgkmcnt(0)
	v_mfma_f32_16x16x32_bf16 v[124:127], v[128:131], v[160:163], v[124:127]
	v_mfma_f32_16x16x32_bf16 v[120:123], v[136:139], v[160:163], v[120:123]
	v_mfma_f32_16x16x32_bf16 v[108:111], v[128:131], v[168:171], v[108:111]
	v_mfma_f32_16x16x32_bf16 v[104:107], v[136:139], v[168:171], v[104:107]
	v_mfma_f32_16x16x32_bf16 v[92:95], v[128:131], v[188:191], v[92:95]
	v_mfma_f32_16x16x32_bf16 v[88:91], v[136:139], v[188:191], v[88:91]
	v_mfma_f32_16x16x32_bf16 v[76:79], v[128:131], v[206:209], v[76:79]
	v_mfma_f32_16x16x32_bf16 v[72:75], v[136:139], v[206:209], v[72:75]
	v_mfma_f32_16x16x32_bf16 v[124:127], v[132:135], v[164:167], v[124:127]
	v_mfma_f32_16x16x32_bf16 v[120:123], v[140:143], v[164:167], v[120:123]
	v_mfma_f32_16x16x32_bf16 v[108:111], v[132:135], v[172:175], v[108:111]
	v_mfma_f32_16x16x32_bf16 v[104:107], v[140:143], v[172:175], v[104:107]
	v_mfma_f32_16x16x32_bf16 v[92:95], v[132:135], v[202:205], v[92:95]
	v_mfma_f32_16x16x32_bf16 v[88:91], v[140:143], v[202:205], v[88:91]
	v_mfma_f32_16x16x32_bf16 v[76:79], v[132:135], v[210:213], v[76:79]
	v_mfma_f32_16x16x32_bf16 v[72:75], v[140:143], v[210:213], v[72:75]
	s_setprio 0
	s_setprio 1
	v_mfma_f32_16x16x32_bf16 v[116:119], v[144:147], v[160:163], v[116:119]
	v_mfma_f32_16x16x32_bf16 v[112:115], v[152:155], v[160:163], v[112:115]
	v_mfma_f32_16x16x32_bf16 v[100:103], v[144:147], v[168:171], v[100:103]
	v_mfma_f32_16x16x32_bf16 v[96:99], v[152:155], v[168:171], v[96:99]
	v_mfma_f32_16x16x32_bf16 v[84:87], v[144:147], v[188:191], v[84:87]
	v_mfma_f32_16x16x32_bf16 v[80:83], v[152:155], v[188:191], v[80:83]
	v_mfma_f32_16x16x32_bf16 v[68:71], v[144:147], v[206:209], v[68:71]
	v_mfma_f32_16x16x32_bf16 v[64:67], v[152:155], v[206:209], v[64:67]
	v_mfma_f32_16x16x32_bf16 v[116:119], v[148:151], v[164:167], v[116:119]
	v_mfma_f32_16x16x32_bf16 v[112:115], v[156:159], v[164:167], v[112:115]
	v_mfma_f32_16x16x32_bf16 v[100:103], v[148:151], v[172:175], v[100:103]
	v_mfma_f32_16x16x32_bf16 v[96:99], v[156:159], v[172:175], v[96:99]
	v_mfma_f32_16x16x32_bf16 v[84:87], v[148:151], v[202:205], v[84:87]
	v_mfma_f32_16x16x32_bf16 v[80:83], v[156:159], v[202:205], v[80:83]
	v_mfma_f32_16x16x32_bf16 v[68:71], v[148:151], v[210:213], v[68:71]
	v_mfma_f32_16x16x32_bf16 v[64:67], v[156:159], v[210:213], v[64:67]
	s_setprio 0
	s_barrier
	s_add_i32 s50, s46, s3
	s_mov_b32 m0, s50
	s_nop 0
	ds_read_b128 v[160:163], v199 offset:16384
	ds_read_b128 v[164:167], v199 offset:17408
	ds_read_b128 v[168:171], v199 offset:18432
	ds_read_b128 v[172:175], v199 offset:19456
	ds_read_b128 v[188:191], v199 offset:20480
	ds_read_b128 v[202:205], v199 offset:21504
	ds_read_b128 v[206:209], v199 offset:22528
	ds_read_b128 v[210:213], v199 offset:23552
	global_load_lds_dwordx4 v176, s[30:31]
	s_add_i32 m0, s50, 0x2000
	s_add_u32 s50, s30, 0x4000
	s_addc_u32 s51, s31, 0
	s_add_i32 s52, s47, s3
	global_load_lds_dwordx4 v178, s[30:31]
	s_mov_b32 m0, s52
	s_nop 0
	global_load_lds_dwordx4 v176, s[50:51]
	s_add_i32 m0, s52, 0x2000
	s_nop 0
	global_load_lds_dwordx4 v178, s[50:51]
	s_mov_b32 m0, s33
	s_nop 0
	global_load_lds_dwordx4 v176, s[34:35]
	s_mov_b32 m0, s36
	s_nop 0
	global_load_lds_dwordx4 v178, s[34:35]
	s_waitcnt vmcnt(8)
	s_waitcnt lgkmcnt(0)
	s_barrier
	s_setprio 1
	s_waitcnt lgkmcnt(0)
	v_mfma_f32_16x16x32_bf16 v[60:63], v[128:131], v[160:163], v[60:63]
	v_mfma_f32_16x16x32_bf16 v[56:59], v[136:139], v[160:163], v[56:59]
	v_mfma_f32_16x16x32_bf16 v[44:47], v[128:131], v[168:171], v[44:47]
	v_mfma_f32_16x16x32_bf16 v[40:43], v[136:139], v[168:171], v[40:43]
	v_mfma_f32_16x16x32_bf16 v[28:31], v[128:131], v[188:191], v[28:31]
	v_mfma_f32_16x16x32_bf16 v[24:27], v[136:139], v[188:191], v[24:27]
	v_mfma_f32_16x16x32_bf16 v[12:15], v[128:131], v[206:209], v[12:15]
	v_mfma_f32_16x16x32_bf16 v[8:11], v[136:139], v[206:209], v[8:11]
	v_mfma_f32_16x16x32_bf16 v[60:63], v[132:135], v[164:167], v[60:63]
	v_mfma_f32_16x16x32_bf16 v[56:59], v[140:143], v[164:167], v[56:59]
	v_mfma_f32_16x16x32_bf16 v[44:47], v[132:135], v[172:175], v[44:47]
	v_mfma_f32_16x16x32_bf16 v[40:43], v[140:143], v[172:175], v[40:43]
	v_mfma_f32_16x16x32_bf16 v[28:31], v[132:135], v[202:205], v[28:31]
	v_mfma_f32_16x16x32_bf16 v[24:27], v[140:143], v[202:205], v[24:27]
	v_mfma_f32_16x16x32_bf16 v[12:15], v[132:135], v[210:213], v[12:15]
	v_mfma_f32_16x16x32_bf16 v[8:11], v[140:143], v[210:213], v[8:11]
	s_setprio 0
	s_setprio 1
	v_mfma_f32_16x16x32_bf16 v[52:55], v[144:147], v[160:163], v[52:55]
	v_mfma_f32_16x16x32_bf16 v[48:51], v[152:155], v[160:163], v[48:51]
	v_mfma_f32_16x16x32_bf16 v[36:39], v[144:147], v[168:171], v[36:39]
	v_mfma_f32_16x16x32_bf16 v[32:35], v[152:155], v[168:171], v[32:35]
	v_mfma_f32_16x16x32_bf16 v[20:23], v[144:147], v[188:191], v[20:23]
	v_mfma_f32_16x16x32_bf16 v[16:19], v[152:155], v[188:191], v[16:19]
	v_mfma_f32_16x16x32_bf16 v[4:7], v[144:147], v[206:209], v[4:7]
	v_mfma_f32_16x16x32_bf16 v[0:3], v[152:155], v[206:209], v[0:3]
	v_mfma_f32_16x16x32_bf16 v[52:55], v[148:151], v[164:167], v[52:55]
	v_mfma_f32_16x16x32_bf16 v[48:51], v[156:159], v[164:167], v[48:51]
	v_mfma_f32_16x16x32_bf16 v[36:39], v[148:151], v[172:175], v[36:39]
	v_mfma_f32_16x16x32_bf16 v[32:35], v[156:159], v[172:175], v[32:35]
	v_mfma_f32_16x16x32_bf16 v[20:23], v[148:151], v[202:205], v[20:23]
	v_mfma_f32_16x16x32_bf16 v[16:19], v[156:159], v[202:205], v[16:19]
	v_mfma_f32_16x16x32_bf16 v[4:7], v[148:151], v[210:213], v[4:7]
	v_mfma_f32_16x16x32_bf16 v[0:3], v[156:159], v[210:213], v[0:3]
	s_setprio 0
	s_barrier
	s_add_i32 s50, 0, 0x18000
	s_add_i32 s51, 0, 0x1c000
	v_add_u32_e32 v140, s50, v196
	v_add_u32_e32 v156, s51, v196
	s_add_u32 s34, s34, 0x4000
	s_addc_u32 s35, s35, 0
	s_mov_b32 m0, s37
	s_nop 0
	global_load_lds_dwordx4 v176, s[34:35]
	s_mov_b32 m0, s38
	s_nop 0
	global_load_lds_dwordx4 v178, s[34:35]
	ds_read_b128 v[128:131], v140
	ds_read_b128 v[132:135], v140 offset:1024
	ds_read_b128 v[136:139], v140 offset:2048
	ds_read_b128 v[140:143], v140 offset:3072
	ds_read_b128 v[144:147], v156
	ds_read_b128 v[148:151], v156 offset:1024
	ds_read_b128 v[152:155], v156 offset:2048
	ds_read_b128 v[156:159], v156 offset:3072
	ds_read_b128 v[160:163], v199 offset:32768
	ds_read_b128 v[164:167], v199 offset:33792
	ds_read_b128 v[168:171], v199 offset:34816
	ds_read_b128 v[172:175], v199 offset:35840
	ds_read_b128 v[188:191], v199 offset:36864
	ds_read_b128 v[202:205], v199 offset:37888
	ds_read_b128 v[206:209], v199 offset:38912
	ds_read_b128 v[210:213], v199 offset:39936
	s_waitcnt vmcnt(8)
	s_waitcnt lgkmcnt(0)
	s_barrier
	s_setprio 1
	s_waitcnt lgkmcnt(0)
	v_mfma_f32_16x16x32_bf16 v[124:127], v[128:131], v[160:163], v[124:127]
	v_mfma_f32_16x16x32_bf16 v[120:123], v[136:139], v[160:163], v[120:123]
	v_mfma_f32_16x16x32_bf16 v[108:111], v[128:131], v[168:171], v[108:111]
	v_mfma_f32_16x16x32_bf16 v[104:107], v[136:139], v[168:171], v[104:107]
	v_mfma_f32_16x16x32_bf16 v[92:95], v[128:131], v[188:191], v[92:95]
	v_mfma_f32_16x16x32_bf16 v[88:91], v[136:139], v[188:191], v[88:91]
	v_mfma_f32_16x16x32_bf16 v[76:79], v[128:131], v[206:209], v[76:79]
	v_mfma_f32_16x16x32_bf16 v[72:75], v[136:139], v[206:209], v[72:75]
	v_mfma_f32_16x16x32_bf16 v[124:127], v[132:135], v[164:167], v[124:127]
	v_mfma_f32_16x16x32_bf16 v[120:123], v[140:143], v[164:167], v[120:123]
	v_mfma_f32_16x16x32_bf16 v[108:111], v[132:135], v[172:175], v[108:111]
	v_mfma_f32_16x16x32_bf16 v[104:107], v[140:143], v[172:175], v[104:107]
	v_mfma_f32_16x16x32_bf16 v[92:95], v[132:135], v[202:205], v[92:95]
	v_mfma_f32_16x16x32_bf16 v[88:91], v[140:143], v[202:205], v[88:91]
	v_mfma_f32_16x16x32_bf16 v[76:79], v[132:135], v[210:213], v[76:79]
	v_mfma_f32_16x16x32_bf16 v[72:75], v[140:143], v[210:213], v[72:75]
	s_setprio 0
	s_setprio 1
	v_mfma_f32_16x16x32_bf16 v[116:119], v[144:147], v[160:163], v[116:119]
	v_mfma_f32_16x16x32_bf16 v[112:115], v[152:155], v[160:163], v[112:115]
	v_mfma_f32_16x16x32_bf16 v[100:103], v[144:147], v[168:171], v[100:103]
	v_mfma_f32_16x16x32_bf16 v[96:99], v[152:155], v[168:171], v[96:99]
	v_mfma_f32_16x16x32_bf16 v[84:87], v[144:147], v[188:191], v[84:87]
	v_mfma_f32_16x16x32_bf16 v[80:83], v[152:155], v[188:191], v[80:83]
	v_mfma_f32_16x16x32_bf16 v[68:71], v[144:147], v[206:209], v[68:71]
	v_mfma_f32_16x16x32_bf16 v[64:67], v[152:155], v[206:209], v[64:67]
	v_mfma_f32_16x16x32_bf16 v[116:119], v[148:151], v[164:167], v[116:119]
	v_mfma_f32_16x16x32_bf16 v[112:115], v[156:159], v[164:167], v[112:115]
	v_mfma_f32_16x16x32_bf16 v[100:103], v[148:151], v[172:175], v[100:103]
	v_mfma_f32_16x16x32_bf16 v[96:99], v[156:159], v[172:175], v[96:99]
	v_mfma_f32_16x16x32_bf16 v[84:87], v[148:151], v[202:205], v[84:87]
	v_mfma_f32_16x16x32_bf16 v[80:83], v[156:159], v[202:205], v[80:83]
	v_mfma_f32_16x16x32_bf16 v[68:71], v[148:151], v[210:213], v[68:71]
	v_mfma_f32_16x16x32_bf16 v[64:67], v[156:159], v[210:213], v[64:67]
	s_setprio 0
	s_barrier
	s_add_u32 s34, s30, 0x8000
	s_addc_u32 s35, s31, 0
	s_add_i32 s50, s50, s3
	s_mov_b32 m0, s50
	s_nop 0
	ds_read_b128 v[160:163], v199 offset:49152
	ds_read_b128 v[164:167], v199 offset:50176
	ds_read_b128 v[168:171], v199 offset:51200
	ds_read_b128 v[172:175], v199 offset:52224
	ds_read_b128 v[188:191], v199 offset:53248
	ds_read_b128 v[202:205], v199 offset:54272
	ds_read_b128 v[206:209], v199 offset:55296
	ds_read_b128 v[210:213], v199 offset:56320
	global_load_lds_dwordx4 v176, s[34:35]
	s_add_i32 m0, s50, 0x2000
	s_add_u32 s30, s30, 0xc000
	s_addc_u32 s31, s31, 0
	global_load_lds_dwordx4 v178, s[34:35]
	s_add_i32 s34, s51, s3
	s_mov_b32 m0, s34
	s_nop 0
	global_load_lds_dwordx4 v176, s[30:31]
	s_add_i32 m0, s34, 0x2000
	s_nop 0
	global_load_lds_dwordx4 v178, s[30:31]
	s_mov_b32 m0, s42
	s_nop 0
	global_load_lds_dwordx4 v176, s[28:29]
	s_mov_b32 m0, s43
	s_nop 0
	global_load_lds_dwordx4 v178, s[28:29]
	s_waitcnt vmcnt(8)
	s_waitcnt lgkmcnt(0)
	s_barrier
	s_setprio 1
	s_waitcnt lgkmcnt(0)
	v_mfma_f32_16x16x32_bf16 v[60:63], v[128:131], v[160:163], v[60:63]
	v_mfma_f32_16x16x32_bf16 v[56:59], v[136:139], v[160:163], v[56:59]
	v_mfma_f32_16x16x32_bf16 v[44:47], v[128:131], v[168:171], v[44:47]
	v_mfma_f32_16x16x32_bf16 v[40:43], v[136:139], v[168:171], v[40:43]
	v_mfma_f32_16x16x32_bf16 v[28:31], v[128:131], v[188:191], v[28:31]
	v_mfma_f32_16x16x32_bf16 v[24:27], v[136:139], v[188:191], v[24:27]
	v_mfma_f32_16x16x32_bf16 v[12:15], v[128:131], v[206:209], v[12:15]
	v_mfma_f32_16x16x32_bf16 v[8:11], v[136:139], v[206:209], v[8:11]
	v_mfma_f32_16x16x32_bf16 v[60:63], v[132:135], v[164:167], v[60:63]
	v_mfma_f32_16x16x32_bf16 v[56:59], v[140:143], v[164:167], v[56:59]
	v_mfma_f32_16x16x32_bf16 v[44:47], v[132:135], v[172:175], v[44:47]
	v_mfma_f32_16x16x32_bf16 v[40:43], v[140:143], v[172:175], v[40:43]
	v_mfma_f32_16x16x32_bf16 v[28:31], v[132:135], v[202:205], v[28:31]
	v_mfma_f32_16x16x32_bf16 v[24:27], v[140:143], v[202:205], v[24:27]
	v_mfma_f32_16x16x32_bf16 v[12:15], v[132:135], v[210:213], v[12:15]
	v_mfma_f32_16x16x32_bf16 v[8:11], v[140:143], v[210:213], v[8:11]
	s_setprio 0
	s_setprio 1
	v_mfma_f32_16x16x32_bf16 v[52:55], v[144:147], v[160:163], v[52:55]
	v_mfma_f32_16x16x32_bf16 v[48:51], v[152:155], v[160:163], v[48:51]
	v_mfma_f32_16x16x32_bf16 v[36:39], v[144:147], v[168:171], v[36:39]
	v_mfma_f32_16x16x32_bf16 v[32:35], v[152:155], v[168:171], v[32:35]
	v_mfma_f32_16x16x32_bf16 v[20:23], v[144:147], v[188:191], v[20:23]
	v_mfma_f32_16x16x32_bf16 v[16:19], v[152:155], v[188:191], v[16:19]
	v_mfma_f32_16x16x32_bf16 v[4:7], v[144:147], v[206:209], v[4:7]
	v_mfma_f32_16x16x32_bf16 v[0:3], v[152:155], v[206:209], v[0:3]
	v_mfma_f32_16x16x32_bf16 v[52:55], v[148:151], v[164:167], v[52:55]
	v_mfma_f32_16x16x32_bf16 v[48:51], v[156:159], v[164:167], v[48:51]
	v_mfma_f32_16x16x32_bf16 v[36:39], v[148:151], v[172:175], v[36:39]
	v_mfma_f32_16x16x32_bf16 v[32:35], v[156:159], v[172:175], v[32:35]
	v_mfma_f32_16x16x32_bf16 v[20:23], v[148:151], v[202:205], v[20:23]
	v_mfma_f32_16x16x32_bf16 v[16:19], v[156:159], v[202:205], v[16:19]
	v_mfma_f32_16x16x32_bf16 v[4:7], v[148:151], v[210:213], v[4:7]
	v_mfma_f32_16x16x32_bf16 v[0:3], v[156:159], v[210:213], v[0:3]
	s_setprio 0
	s_barrier
	s_add_i32 s49, s49, 2
	s_add_u32 s26, s26, 0x10000
	s_addc_u32 s27, s27, 0
	s_add_u32 s25, s25, 0x10000
	s_addc_u32 s48, s48, 0
	s_cmp_gt_u32 s49, 61
	s_cbranch_scc0 .LBB0_469
	s_and_b64 vcc, exec, s[12:13]
	s_cbranch_vccz .LBB0_472
	s_barrier

.LBB0_640:
	s_add_u32 s22, s20, 0x4000
	s_addc_u32 s23, s21, 0
	s_cmp_eq_u32 s51, 60
	s_cselect_b32 s26, s19, s22
	s_cselect_b32 s27, s11, s23
	s_cselect_b32 s24, s48, s49
	s_cselect_b32 s25, s13, s50
	s_add_u32 s22, s26, 0x8000
	s_addc_u32 s23, s27, 0
	s_add_i32 m0, s30, 0xc000
	s_nop 0
	global_load_lds_dwordx4 v160, s[20:21]
	s_add_i32 m0, s30, 0xe000
	s_nop 0
	global_load_lds_dwordx4 v162, s[20:21]
	ds_read_b128 v[56:59], v179
	ds_read_b128 v[60:63], v179 offset:1024
	ds_read_b128 v[64:67], v179 offset:2048
	ds_read_b128 v[68:71], v179 offset:3072
	ds_read_b128 v[144:147], v180
	ds_read_b128 v[148:151], v180 offset:1024
	ds_read_b128 v[152:155], v180 offset:2048
	ds_read_b128 v[156:159], v180 offset:3072
	ds_read_b128 v[172:175], v181
	ds_read_b128 v[182:185], v181 offset:1024
	ds_read_b128 v[186:189], v181 offset:2048
	ds_read_b128 v[190:193], v181 offset:3072
	ds_read_b128 v[196:199], v181 offset:4096
	ds_read_b128 v[200:203], v181 offset:5120
	ds_read_b128 v[204:207], v181 offset:6144
	ds_read_b128 v[208:211], v181 offset:7168
	s_waitcnt vmcnt(8)
	s_waitcnt lgkmcnt(0)
	s_barrier
	s_setprio 1
	s_waitcnt lgkmcnt(0)
	v_mfma_f32_16x16x32_bf16 v[140:143], v[56:59], v[172:175], v[140:143]
	v_mfma_f32_16x16x32_bf16 v[136:139], v[64:67], v[172:175], v[136:139]
	v_mfma_f32_16x16x32_bf16 v[124:127], v[56:59], v[186:189], v[124:127]
	v_mfma_f32_16x16x32_bf16 v[120:123], v[64:67], v[186:189], v[120:123]
	v_mfma_f32_16x16x32_bf16 v[108:111], v[56:59], v[196:199], v[108:111]
	v_mfma_f32_16x16x32_bf16 v[104:107], v[64:67], v[196:199], v[104:107]
	v_mfma_f32_16x16x32_bf16 v[92:95], v[56:59], v[204:207], v[92:95]
	v_mfma_f32_16x16x32_bf16 v[88:91], v[64:67], v[204:207], v[88:91]
	v_mfma_f32_16x16x32_bf16 v[140:143], v[60:63], v[182:185], v[140:143]
	v_mfma_f32_16x16x32_bf16 v[136:139], v[68:71], v[182:185], v[136:139]
	v_mfma_f32_16x16x32_bf16 v[124:127], v[60:63], v[190:193], v[124:127]
	v_mfma_f32_16x16x32_bf16 v[120:123], v[68:71], v[190:193], v[120:123]
	v_mfma_f32_16x16x32_bf16 v[108:111], v[60:63], v[200:203], v[108:111]
	v_mfma_f32_16x16x32_bf16 v[104:107], v[68:71], v[200:203], v[104:107]
	v_mfma_f32_16x16x32_bf16 v[92:95], v[60:63], v[208:211], v[92:95]
	v_mfma_f32_16x16x32_bf16 v[88:91], v[68:71], v[208:211], v[88:91]
	s_setprio 0
	s_setprio 1
	v_mfma_f32_16x16x32_bf16 v[132:135], v[144:147], v[172:175], v[132:135]
	v_mfma_f32_16x16x32_bf16 v[128:131], v[152:155], v[172:175], v[128:131]
	v_mfma_f32_16x16x32_bf16 v[116:119], v[144:147], v[186:189], v[116:119]
	v_mfma_f32_16x16x32_bf16 v[112:115], v[152:155], v[186:189], v[112:115]
	v_mfma_f32_16x16x32_bf16 v[100:103], v[144:147], v[196:199], v[100:103]
	v_mfma_f32_16x16x32_bf16 v[96:99], v[152:155], v[196:199], v[96:99]
	v_mfma_f32_16x16x32_bf16 v[84:87], v[144:147], v[204:207], v[84:87]
	v_mfma_f32_16x16x32_bf16 v[80:83], v[152:155], v[204:207], v[80:83]
	v_mfma_f32_16x16x32_bf16 v[132:135], v[148:151], v[182:185], v[132:135]
	v_mfma_f32_16x16x32_bf16 v[128:131], v[156:159], v[182:185], v[128:131]
	v_mfma_f32_16x16x32_bf16 v[116:119], v[148:151], v[190:193], v[116:119]
	v_mfma_f32_16x16x32_bf16 v[112:115], v[156:159], v[190:193], v[112:115]
	v_mfma_f32_16x16x32_bf16 v[100:103], v[148:151], v[200:203], v[100:103]
	v_mfma_f32_16x16x32_bf16 v[96:99], v[156:159], v[200:203], v[96:99]
	v_mfma_f32_16x16x32_bf16 v[84:87], v[148:151], v[208:211], v[84:87]
	v_mfma_f32_16x16x32_bf16 v[80:83], v[156:159], v[208:211], v[80:83]
	s_setprio 0
	s_barrier
	s_add_i32 s52, s46, s3
	s_mov_b32 m0, s52
	s_nop 0
	ds_read_b128 v[172:175], v181 offset:16384
	ds_read_b128 v[182:185], v181 offset:17408
	ds_read_b128 v[186:189], v181 offset:18432
	ds_read_b128 v[190:193], v181 offset:19456
	ds_read_b128 v[196:199], v181 offset:20480
	ds_read_b128 v[200:203], v181 offset:21504
	ds_read_b128 v[204:207], v181 offset:22528
	ds_read_b128 v[208:211], v181 offset:23552
	global_load_lds_dwordx4 v160, s[24:25]
	s_add_i32 m0, s52, 0x2000
	s_add_u32 s52, s24, 0x4000
	s_addc_u32 s53, s25, 0
	s_add_i32 s54, s47, s3
	global_load_lds_dwordx4 v162, s[24:25]
	s_mov_b32 m0, s54
	s_nop 0
	global_load_lds_dwordx4 v160, s[52:53]
	s_add_i32 m0, s54, 0x2000
	s_nop 0
	global_load_lds_dwordx4 v162, s[52:53]
	s_mov_b32 m0, s30
	s_nop 0
	global_load_lds_dwordx4 v160, s[26:27]
	s_mov_b32 m0, s31
	s_nop 0
	global_load_lds_dwordx4 v162, s[26:27]
	s_waitcnt vmcnt(8)
	s_waitcnt lgkmcnt(0)
	s_barrier
	s_setprio 1
	s_waitcnt lgkmcnt(0)
	v_mfma_f32_16x16x32_bf16 v[76:79], v[56:59], v[172:175], v[76:79]
	v_mfma_f32_16x16x32_bf16 v[72:75], v[64:67], v[172:175], v[72:75]
	v_mfma_f32_16x16x32_bf16 v[44:47], v[56:59], v[186:189], v[44:47]
	v_mfma_f32_16x16x32_bf16 v[40:43], v[64:67], v[186:189], v[40:43]
	v_mfma_f32_16x16x32_bf16 v[28:31], v[56:59], v[196:199], v[28:31]
	v_mfma_f32_16x16x32_bf16 v[24:27], v[64:67], v[196:199], v[24:27]
	v_mfma_f32_16x16x32_bf16 v[12:15], v[56:59], v[204:207], v[12:15]
	v_mfma_f32_16x16x32_bf16 v[8:11], v[64:67], v[204:207], v[8:11]
	v_mfma_f32_16x16x32_bf16 v[76:79], v[60:63], v[182:185], v[76:79]
	v_mfma_f32_16x16x32_bf16 v[72:75], v[68:71], v[182:185], v[72:75]
	v_mfma_f32_16x16x32_bf16 v[44:47], v[60:63], v[190:193], v[44:47]
	v_mfma_f32_16x16x32_bf16 v[40:43], v[68:71], v[190:193], v[40:43]
	v_mfma_f32_16x16x32_bf16 v[28:31], v[60:63], v[200:203], v[28:31]
	v_mfma_f32_16x16x32_bf16 v[24:27], v[68:71], v[200:203], v[24:27]
	v_mfma_f32_16x16x32_bf16 v[12:15], v[60:63], v[208:211], v[12:15]
	v_mfma_f32_16x16x32_bf16 v[8:11], v[68:71], v[208:211], v[8:11]
	s_setprio 0
	s_setprio 1
	v_mfma_f32_16x16x32_bf16 v[52:55], v[144:147], v[172:175], v[52:55]
	v_mfma_f32_16x16x32_bf16 v[48:51], v[152:155], v[172:175], v[48:51]
	v_mfma_f32_16x16x32_bf16 v[36:39], v[144:147], v[186:189], v[36:39]
	v_mfma_f32_16x16x32_bf16 v[32:35], v[152:155], v[186:189], v[32:35]
	v_mfma_f32_16x16x32_bf16 v[20:23], v[144:147], v[196:199], v[20:23]
	v_mfma_f32_16x16x32_bf16 v[16:19], v[152:155], v[196:199], v[16:19]
	v_mfma_f32_16x16x32_bf16 v[4:7], v[144:147], v[204:207], v[4:7]
	v_mfma_f32_16x16x32_bf16 v[0:3], v[152:155], v[204:207], v[0:3]
	v_mfma_f32_16x16x32_bf16 v[52:55], v[148:151], v[182:185], v[52:55]
	v_mfma_f32_16x16x32_bf16 v[48:51], v[156:159], v[182:185], v[48:51]
	v_mfma_f32_16x16x32_bf16 v[36:39], v[148:151], v[190:193], v[36:39]
	v_mfma_f32_16x16x32_bf16 v[32:35], v[156:159], v[190:193], v[32:35]
	v_mfma_f32_16x16x32_bf16 v[20:23], v[148:151], v[200:203], v[20:23]
	v_mfma_f32_16x16x32_bf16 v[16:19], v[156:159], v[200:203], v[16:19]
	v_mfma_f32_16x16x32_bf16 v[4:7], v[148:151], v[208:211], v[4:7]
	v_mfma_f32_16x16x32_bf16 v[0:3], v[156:159], v[208:211], v[0:3]
	s_setprio 0
	s_barrier
	s_add_i32 s52, 0, 0x18000
	s_add_i32 s53, 0, 0x1c000
	v_add_u32_e32 v68, s52, v178
	v_add_u32_e32 v156, s53, v178
	s_add_u32 s26, s26, 0x4000
	s_addc_u32 s27, s27, 0
	s_mov_b32 m0, s33
	s_nop 0
	global_load_lds_dwordx4 v160, s[26:27]
	s_mov_b32 m0, s34
	s_nop 0
	global_load_lds_dwordx4 v162, s[26:27]
	ds_read_b128 v[56:59], v68
	ds_read_b128 v[60:63], v68 offset:1024
	ds_read_b128 v[64:67], v68 offset:2048
	ds_read_b128 v[68:71], v68 offset:3072
	ds_read_b128 v[144:147], v156
	ds_read_b128 v[148:151], v156 offset:1024
	ds_read_b128 v[152:155], v156 offset:2048
	ds_read_b128 v[156:159], v156 offset:3072
	ds_read_b128 v[172:175], v181 offset:32768
	ds_read_b128 v[182:185], v181 offset:33792
	ds_read_b128 v[186:189], v181 offset:34816
	ds_read_b128 v[190:193], v181 offset:35840
	ds_read_b128 v[196:199], v181 offset:36864
	ds_read_b128 v[200:203], v181 offset:37888
	ds_read_b128 v[204:207], v181 offset:38912
	ds_read_b128 v[208:211], v181 offset:39936
	s_waitcnt vmcnt(8)
	s_waitcnt lgkmcnt(0)
	s_barrier
	s_setprio 1
	s_waitcnt lgkmcnt(0)
	v_mfma_f32_16x16x32_bf16 v[140:143], v[56:59], v[172:175], v[140:143]
	v_mfma_f32_16x16x32_bf16 v[136:139], v[64:67], v[172:175], v[136:139]
	v_mfma_f32_16x16x32_bf16 v[124:127], v[56:59], v[186:189], v[124:127]
	v_mfma_f32_16x16x32_bf16 v[120:123], v[64:67], v[186:189], v[120:123]
	v_mfma_f32_16x16x32_bf16 v[108:111], v[56:59], v[196:199], v[108:111]
	v_mfma_f32_16x16x32_bf16 v[104:107], v[64:67], v[196:199], v[104:107]
	v_mfma_f32_16x16x32_bf16 v[92:95], v[56:59], v[204:207], v[92:95]
	v_mfma_f32_16x16x32_bf16 v[88:91], v[64:67], v[204:207], v[88:91]
	v_mfma_f32_16x16x32_bf16 v[140:143], v[60:63], v[182:185], v[140:143]
	v_mfma_f32_16x16x32_bf16 v[136:139], v[68:71], v[182:185], v[136:139]
	v_mfma_f32_16x16x32_bf16 v[124:127], v[60:63], v[190:193], v[124:127]
	v_mfma_f32_16x16x32_bf16 v[120:123], v[68:71], v[190:193], v[120:123]
	v_mfma_f32_16x16x32_bf16 v[108:111], v[60:63], v[200:203], v[108:111]
	v_mfma_f32_16x16x32_bf16 v[104:107], v[68:71], v[200:203], v[104:107]
	v_mfma_f32_16x16x32_bf16 v[92:95], v[60:63], v[208:211], v[92:95]
	v_mfma_f32_16x16x32_bf16 v[88:91], v[68:71], v[208:211], v[88:91]
	s_setprio 0
	s_setprio 1
	v_mfma_f32_16x16x32_bf16 v[132:135], v[144:147], v[172:175], v[132:135]
	v_mfma_f32_16x16x32_bf16 v[128:131], v[152:155], v[172:175], v[128:131]
	v_mfma_f32_16x16x32_bf16 v[116:119], v[144:147], v[186:189], v[116:119]
	v_mfma_f32_16x16x32_bf16 v[112:115], v[152:155], v[186:189], v[112:115]
	v_mfma_f32_16x16x32_bf16 v[100:103], v[144:147], v[196:199], v[100:103]
	v_mfma_f32_16x16x32_bf16 v[96:99], v[152:155], v[196:199], v[96:99]
	v_mfma_f32_16x16x32_bf16 v[84:87], v[144:147], v[204:207], v[84:87]
	v_mfma_f32_16x16x32_bf16 v[80:83], v[152:155], v[204:207], v[80:83]
	v_mfma_f32_16x16x32_bf16 v[132:135], v[148:151], v[182:185], v[132:135]
	v_mfma_f32_16x16x32_bf16 v[128:131], v[156:159], v[182:185], v[128:131]
	v_mfma_f32_16x16x32_bf16 v[116:119], v[148:151], v[190:193], v[116:119]
	v_mfma_f32_16x16x32_bf16 v[112:115], v[156:159], v[190:193], v[112:115]
	v_mfma_f32_16x16x32_bf16 v[100:103], v[148:151], v[200:203], v[100:103]
	v_mfma_f32_16x16x32_bf16 v[96:99], v[156:159], v[200:203], v[96:99]
	v_mfma_f32_16x16x32_bf16 v[84:87], v[148:151], v[208:211], v[84:87]
	v_mfma_f32_16x16x32_bf16 v[80:83], v[156:159], v[208:211], v[80:83]
	s_setprio 0
	s_barrier
	s_add_u32 s26, s24, 0x8000
	s_addc_u32 s27, s25, 0
	s_add_i32 s52, s52, s3
	s_mov_b32 m0, s52
	s_nop 0
	ds_read_b128 v[172:175], v181 offset:49152
	ds_read_b128 v[182:185], v181 offset:50176
	ds_read_b128 v[186:189], v181 offset:51200
	ds_read_b128 v[190:193], v181 offset:52224
	ds_read_b128 v[196:199], v181 offset:53248
	ds_read_b128 v[200:203], v181 offset:54272
	ds_read_b128 v[204:207], v181 offset:55296
	ds_read_b128 v[208:211], v181 offset:56320
	global_load_lds_dwordx4 v160, s[26:27]
	s_add_i32 m0, s52, 0x2000
	s_add_u32 s24, s24, 0xc000
	s_addc_u32 s25, s25, 0
	global_load_lds_dwordx4 v162, s[26:27]
	s_add_i32 s26, s53, s3
	s_mov_b32 m0, s26
	s_nop 0
	global_load_lds_dwordx4 v160, s[24:25]
	s_add_i32 m0, s26, 0x2000
	s_nop 0
	global_load_lds_dwordx4 v162, s[24:25]
	s_mov_b32 m0, s39
	s_nop 0
	global_load_lds_dwordx4 v160, s[22:23]
	s_mov_b32 m0, s40
	s_nop 0
	global_load_lds_dwordx4 v162, s[22:23]
	s_waitcnt vmcnt(8)
	s_waitcnt lgkmcnt(0)
	s_barrier
	s_setprio 1
	s_waitcnt lgkmcnt(0)
	v_mfma_f32_16x16x32_bf16 v[76:79], v[56:59], v[172:175], v[76:79]
	v_mfma_f32_16x16x32_bf16 v[72:75], v[64:67], v[172:175], v[72:75]
	v_mfma_f32_16x16x32_bf16 v[44:47], v[56:59], v[186:189], v[44:47]
	v_mfma_f32_16x16x32_bf16 v[40:43], v[64:67], v[186:189], v[40:43]
	v_mfma_f32_16x16x32_bf16 v[28:31], v[56:59], v[196:199], v[28:31]
	v_mfma_f32_16x16x32_bf16 v[24:27], v[64:67], v[196:199], v[24:27]
	v_mfma_f32_16x16x32_bf16 v[12:15], v[56:59], v[204:207], v[12:15]
	v_mfma_f32_16x16x32_bf16 v[8:11], v[64:67], v[204:207], v[8:11]
	v_mfma_f32_16x16x32_bf16 v[76:79], v[60:63], v[182:185], v[76:79]
	v_mfma_f32_16x16x32_bf16 v[72:75], v[68:71], v[182:185], v[72:75]
	v_mfma_f32_16x16x32_bf16 v[44:47], v[60:63], v[190:193], v[44:47]
	v_mfma_f32_16x16x32_bf16 v[40:43], v[68:71], v[190:193], v[40:43]
	v_mfma_f32_16x16x32_bf16 v[28:31], v[60:63], v[200:203], v[28:31]
	v_mfma_f32_16x16x32_bf16 v[24:27], v[68:71], v[200:203], v[24:27]
	v_mfma_f32_16x16x32_bf16 v[12:15], v[60:63], v[208:211], v[12:15]
	v_mfma_f32_16x16x32_bf16 v[8:11], v[68:71], v[208:211], v[8:11]
	s_setprio 0
	s_setprio 1
	v_mfma_f32_16x16x32_bf16 v[52:55], v[144:147], v[172:175], v[52:55]
	v_mfma_f32_16x16x32_bf16 v[48:51], v[152:155], v[172:175], v[48:51]
	v_mfma_f32_16x16x32_bf16 v[36:39], v[144:147], v[186:189], v[36:39]
	v_mfma_f32_16x16x32_bf16 v[32:35], v[152:155], v[186:189], v[32:35]
	v_mfma_f32_16x16x32_bf16 v[20:23], v[144:147], v[196:199], v[20:23]
	v_mfma_f32_16x16x32_bf16 v[16:19], v[152:155], v[196:199], v[16:19]
	v_mfma_f32_16x16x32_bf16 v[4:7], v[144:147], v[204:207], v[4:7]
	v_mfma_f32_16x16x32_bf16 v[0:3], v[152:155], v[204:207], v[0:3]
	v_mfma_f32_16x16x32_bf16 v[52:55], v[148:151], v[182:185], v[52:55]
	v_mfma_f32_16x16x32_bf16 v[48:51], v[156:159], v[182:185], v[48:51]
	v_mfma_f32_16x16x32_bf16 v[36:39], v[148:151], v[190:193], v[36:39]
	v_mfma_f32_16x16x32_bf16 v[32:35], v[156:159], v[190:193], v[32:35]
	v_mfma_f32_16x16x32_bf16 v[20:23], v[148:151], v[200:203], v[20:23]
	v_mfma_f32_16x16x32_bf16 v[16:19], v[156:159], v[200:203], v[16:19]
	v_mfma_f32_16x16x32_bf16 v[4:7], v[148:151], v[208:211], v[4:7]
	v_mfma_f32_16x16x32_bf16 v[0:3], v[156:159], v[208:211], v[0:3]
	s_setprio 0
	s_barrier
	s_add_i32 s51, s51, 2
	s_add_u32 s20, s20, 0x10000
	s_addc_u32 s21, s21, 0
	s_add_u32 s49, s49, 0x10000
	s_addc_u32 s50, s50, 0
	s_cmp_gt_u32 s51, 61
	s_cbranch_scc0 .LBB0_640
	s_and_b64 vcc, exec, s[6:7]
	s_cbranch_vccz .LBB0_643
	s_barrier

.LBB0_716:
	s_add_u32 s20, s18, 0x4000
	s_addc_u32 s21, s19, 0
	s_cmp_eq_u32 s48, 60
	s_cselect_b32 s24, s44, s20
	s_cselect_b32 s25, s9, s21
	s_cselect_b32 s22, s45, s46
	s_cselect_b32 s23, s11, s47
	s_add_u32 s20, s24, 0x8000
	s_addc_u32 s21, s25, 0
	s_add_i32 m0, s28, 0xc000
	s_nop 0
	global_load_lds_dwordx4 v128, s[18:19]
	s_add_i32 m0, s28, 0xe000
	s_nop 0
	global_load_lds_dwordx4 v130, s[18:19]
	ds_read_b128 v[138:141], v145
	ds_read_b128 v[148:151], v145 offset:1024
	ds_read_b128 v[152:155], v145 offset:2048
	ds_read_b128 v[156:159], v145 offset:3072
	ds_read_b128 v[160:163], v146
	ds_read_b128 v[164:167], v146 offset:1024
	ds_read_b128 v[168:171], v146 offset:2048
	ds_read_b128 v[172:175], v146 offset:3072
	ds_read_b128 v[176:179], v147
	ds_read_b128 v[180:183], v147 offset:1024
	ds_read_b128 v[184:187], v147 offset:2048
	ds_read_b128 v[188:191], v147 offset:3072
	ds_read_b128 v[192:195], v147 offset:4096
	ds_read_b128 v[196:199], v147 offset:5120
	ds_read_b128 v[200:203], v147 offset:6144
	ds_read_b128 v[204:207], v147 offset:7168
	s_waitcnt vmcnt(8)
	s_waitcnt lgkmcnt(0)
	s_barrier
	s_setprio 1
	s_waitcnt lgkmcnt(0)
	v_mfma_f32_16x16x32_bf16 v[124:127], v[138:141], v[176:179], v[124:127]
	v_mfma_f32_16x16x32_bf16 v[120:123], v[152:155], v[176:179], v[120:123]
	v_mfma_f32_16x16x32_bf16 v[116:119], v[138:141], v[184:187], v[116:119]
	v_mfma_f32_16x16x32_bf16 v[104:107], v[152:155], v[184:187], v[104:107]
	v_mfma_f32_16x16x32_bf16 v[92:95], v[138:141], v[192:195], v[92:95]
	v_mfma_f32_16x16x32_bf16 v[88:91], v[152:155], v[192:195], v[88:91]
	v_mfma_f32_16x16x32_bf16 v[84:87], v[138:141], v[200:203], v[84:87]
	v_mfma_f32_16x16x32_bf16 v[72:75], v[152:155], v[200:203], v[72:75]
	v_mfma_f32_16x16x32_bf16 v[124:127], v[148:151], v[180:183], v[124:127]
	v_mfma_f32_16x16x32_bf16 v[120:123], v[156:159], v[180:183], v[120:123]
	v_mfma_f32_16x16x32_bf16 v[116:119], v[148:151], v[188:191], v[116:119]
	v_mfma_f32_16x16x32_bf16 v[104:107], v[156:159], v[188:191], v[104:107]
	v_mfma_f32_16x16x32_bf16 v[92:95], v[148:151], v[196:199], v[92:95]
	v_mfma_f32_16x16x32_bf16 v[88:91], v[156:159], v[196:199], v[88:91]
	v_mfma_f32_16x16x32_bf16 v[84:87], v[148:151], v[204:207], v[84:87]
	v_mfma_f32_16x16x32_bf16 v[72:75], v[156:159], v[204:207], v[72:75]
	s_setprio 0
	s_setprio 1
	v_mfma_f32_16x16x32_bf16 v[112:115], v[160:163], v[176:179], v[112:115]
	v_mfma_f32_16x16x32_bf16 v[108:111], v[168:171], v[176:179], v[108:111]
	v_mfma_f32_16x16x32_bf16 v[100:103], v[160:163], v[184:187], v[100:103]
	v_mfma_f32_16x16x32_bf16 v[96:99], v[168:171], v[184:187], v[96:99]
	v_mfma_f32_16x16x32_bf16 v[80:83], v[160:163], v[192:195], v[80:83]
	v_mfma_f32_16x16x32_bf16 v[76:79], v[168:171], v[192:195], v[76:79]
	v_mfma_f32_16x16x32_bf16 v[68:71], v[160:163], v[200:203], v[68:71]
	v_mfma_f32_16x16x32_bf16 v[64:67], v[168:171], v[200:203], v[64:67]
	v_mfma_f32_16x16x32_bf16 v[112:115], v[164:167], v[180:183], v[112:115]
	v_mfma_f32_16x16x32_bf16 v[108:111], v[172:175], v[180:183], v[108:111]
	v_mfma_f32_16x16x32_bf16 v[100:103], v[164:167], v[188:191], v[100:103]
	v_mfma_f32_16x16x32_bf16 v[96:99], v[172:175], v[188:191], v[96:99]
	v_mfma_f32_16x16x32_bf16 v[80:83], v[164:167], v[196:199], v[80:83]
	v_mfma_f32_16x16x32_bf16 v[76:79], v[172:175], v[196:199], v[76:79]
	v_mfma_f32_16x16x32_bf16 v[68:71], v[164:167], v[204:207], v[68:71]
	v_mfma_f32_16x16x32_bf16 v[64:67], v[172:175], v[204:207], v[64:67]
	s_setprio 0
	s_barrier
	s_add_i32 s49, s42, s3
	s_mov_b32 m0, s49
	s_nop 0
	ds_read_b128 v[176:179], v147 offset:16384
	ds_read_b128 v[180:183], v147 offset:17408
	ds_read_b128 v[184:187], v147 offset:18432
	ds_read_b128 v[188:191], v147 offset:19456
	ds_read_b128 v[192:195], v147 offset:20480
	ds_read_b128 v[196:199], v147 offset:21504
	ds_read_b128 v[200:203], v147 offset:22528
	ds_read_b128 v[204:207], v147 offset:23552
	global_load_lds_dwordx4 v128, s[22:23]
	s_add_i32 m0, s49, 0x2000
	s_add_u32 s50, s22, 0x4000
	s_addc_u32 s51, s23, 0
	s_add_i32 s49, s43, s3
	global_load_lds_dwordx4 v130, s[22:23]
	s_mov_b32 m0, s49
	s_nop 0
	global_load_lds_dwordx4 v128, s[50:51]
	s_add_i32 m0, s49, 0x2000
	s_nop 0
	global_load_lds_dwordx4 v130, s[50:51]
	s_mov_b32 m0, s28
	s_nop 0
	global_load_lds_dwordx4 v128, s[24:25]
	s_mov_b32 m0, s29
	s_nop 0
	global_load_lds_dwordx4 v130, s[24:25]
	s_waitcnt vmcnt(8)
	s_waitcnt lgkmcnt(0)
	s_barrier
	s_setprio 1
	s_waitcnt lgkmcnt(0)
	v_mfma_f32_16x16x32_bf16 v[60:63], v[138:141], v[176:179], v[60:63]
	v_mfma_f32_16x16x32_bf16 v[56:59], v[152:155], v[176:179], v[56:59]
	v_mfma_f32_16x16x32_bf16 v[48:51], v[138:141], v[184:187], v[48:51]
	v_mfma_f32_16x16x32_bf16 v[40:43], v[152:155], v[184:187], v[40:43]
	v_mfma_f32_16x16x32_bf16 v[28:31], v[138:141], v[192:195], v[28:31]
	v_mfma_f32_16x16x32_bf16 v[24:27], v[152:155], v[192:195], v[24:27]
	v_mfma_f32_16x16x32_bf16 v[16:19], v[138:141], v[200:203], v[16:19]
	v_mfma_f32_16x16x32_bf16 v[8:11], v[152:155], v[200:203], v[8:11]
	v_mfma_f32_16x16x32_bf16 v[60:63], v[148:151], v[180:183], v[60:63]
	v_mfma_f32_16x16x32_bf16 v[56:59], v[156:159], v[180:183], v[56:59]
	v_mfma_f32_16x16x32_bf16 v[48:51], v[148:151], v[188:191], v[48:51]
	v_mfma_f32_16x16x32_bf16 v[40:43], v[156:159], v[188:191], v[40:43]
	v_mfma_f32_16x16x32_bf16 v[28:31], v[148:151], v[196:199], v[28:31]
	v_mfma_f32_16x16x32_bf16 v[24:27], v[156:159], v[196:199], v[24:27]
	v_mfma_f32_16x16x32_bf16 v[16:19], v[148:151], v[204:207], v[16:19]
	v_mfma_f32_16x16x32_bf16 v[8:11], v[156:159], v[204:207], v[8:11]
	s_setprio 0
	s_setprio 1
	v_mfma_f32_16x16x32_bf16 v[52:55], v[160:163], v[176:179], v[52:55]
	v_mfma_f32_16x16x32_bf16 v[44:47], v[168:171], v[176:179], v[44:47]
	v_mfma_f32_16x16x32_bf16 v[36:39], v[160:163], v[184:187], v[36:39]
	v_mfma_f32_16x16x32_bf16 v[32:35], v[168:171], v[184:187], v[32:35]
	v_mfma_f32_16x16x32_bf16 v[20:23], v[160:163], v[192:195], v[20:23]
	v_mfma_f32_16x16x32_bf16 v[12:15], v[168:171], v[192:195], v[12:15]
	v_mfma_f32_16x16x32_bf16 v[4:7], v[160:163], v[200:203], v[4:7]
	v_mfma_f32_16x16x32_bf16 v[0:3], v[168:171], v[200:203], v[0:3]
	v_mfma_f32_16x16x32_bf16 v[52:55], v[164:167], v[180:183], v[52:55]
	v_mfma_f32_16x16x32_bf16 v[44:47], v[172:175], v[180:183], v[44:47]
	v_mfma_f32_16x16x32_bf16 v[36:39], v[164:167], v[188:191], v[36:39]
	v_mfma_f32_16x16x32_bf16 v[32:35], v[172:175], v[188:191], v[32:35]
	v_mfma_f32_16x16x32_bf16 v[20:23], v[164:167], v[196:199], v[20:23]
	v_mfma_f32_16x16x32_bf16 v[12:15], v[172:175], v[196:199], v[12:15]
	v_mfma_f32_16x16x32_bf16 v[4:7], v[164:167], v[204:207], v[4:7]
	v_mfma_f32_16x16x32_bf16 v[0:3], v[172:175], v[204:207], v[0:3]
	s_setprio 0
	s_barrier
	s_add_i32 s49, 0, 0x18000
	v_add_u32_e32 v132, s49, v144
	s_add_i32 s50, 0, 0x1c000
	s_add_u32 s24, s24, 0x4000
	s_addc_u32 s25, s25, 0
	s_mov_b32 m0, s30
	s_nop 0
	global_load_lds_dwordx4 v128, s[24:25]
	s_mov_b32 m0, s31
	s_nop 0
	global_load_lds_dwordx4 v130, s[24:25]
	ds_read_b128 v[138:141], v132
	ds_read_b128 v[148:151], v132 offset:1024
	ds_read_b128 v[152:155], v132 offset:2048
	ds_read_b128 v[156:159], v132 offset:3072
	v_add_u32_e32 v132, s50, v144
	ds_read_b128 v[160:163], v132
	ds_read_b128 v[164:167], v132 offset:1024
	ds_read_b128 v[168:171], v132 offset:2048
	ds_read_b128 v[172:175], v132 offset:3072
	ds_read_b128 v[176:179], v147 offset:32768
	ds_read_b128 v[180:183], v147 offset:33792
	ds_read_b128 v[184:187], v147 offset:34816
	ds_read_b128 v[188:191], v147 offset:35840
	ds_read_b128 v[192:195], v147 offset:36864
	ds_read_b128 v[196:199], v147 offset:37888
	ds_read_b128 v[200:203], v147 offset:38912
	ds_read_b128 v[204:207], v147 offset:39936
	s_waitcnt vmcnt(8)
	s_waitcnt lgkmcnt(0)
	s_barrier
	s_setprio 1
	s_waitcnt lgkmcnt(0)
	v_mfma_f32_16x16x32_bf16 v[124:127], v[138:141], v[176:179], v[124:127]
	v_mfma_f32_16x16x32_bf16 v[120:123], v[152:155], v[176:179], v[120:123]
	v_mfma_f32_16x16x32_bf16 v[116:119], v[138:141], v[184:187], v[116:119]
	v_mfma_f32_16x16x32_bf16 v[104:107], v[152:155], v[184:187], v[104:107]
	v_mfma_f32_16x16x32_bf16 v[92:95], v[138:141], v[192:195], v[92:95]
	v_mfma_f32_16x16x32_bf16 v[88:91], v[152:155], v[192:195], v[88:91]
	v_mfma_f32_16x16x32_bf16 v[84:87], v[138:141], v[200:203], v[84:87]
	v_mfma_f32_16x16x32_bf16 v[72:75], v[152:155], v[200:203], v[72:75]
	v_mfma_f32_16x16x32_bf16 v[124:127], v[148:151], v[180:183], v[124:127]
	v_mfma_f32_16x16x32_bf16 v[120:123], v[156:159], v[180:183], v[120:123]
	v_mfma_f32_16x16x32_bf16 v[116:119], v[148:151], v[188:191], v[116:119]
	v_mfma_f32_16x16x32_bf16 v[104:107], v[156:159], v[188:191], v[104:107]
	v_mfma_f32_16x16x32_bf16 v[92:95], v[148:151], v[196:199], v[92:95]
	v_mfma_f32_16x16x32_bf16 v[88:91], v[156:159], v[196:199], v[88:91]
	v_mfma_f32_16x16x32_bf16 v[84:87], v[148:151], v[204:207], v[84:87]
	v_mfma_f32_16x16x32_bf16 v[72:75], v[156:159], v[204:207], v[72:75]
	s_setprio 0
	s_setprio 1
	v_mfma_f32_16x16x32_bf16 v[112:115], v[160:163], v[176:179], v[112:115]
	v_mfma_f32_16x16x32_bf16 v[108:111], v[168:171], v[176:179], v[108:111]
	v_mfma_f32_16x16x32_bf16 v[100:103], v[160:163], v[184:187], v[100:103]
	v_mfma_f32_16x16x32_bf16 v[96:99], v[168:171], v[184:187], v[96:99]
	v_mfma_f32_16x16x32_bf16 v[80:83], v[160:163], v[192:195], v[80:83]
	v_mfma_f32_16x16x32_bf16 v[76:79], v[168:171], v[192:195], v[76:79]
	v_mfma_f32_16x16x32_bf16 v[68:71], v[160:163], v[200:203], v[68:71]
	v_mfma_f32_16x16x32_bf16 v[64:67], v[168:171], v[200:203], v[64:67]
	v_mfma_f32_16x16x32_bf16 v[112:115], v[164:167], v[180:183], v[112:115]
	v_mfma_f32_16x16x32_bf16 v[108:111], v[172:175], v[180:183], v[108:111]
	v_mfma_f32_16x16x32_bf16 v[100:103], v[164:167], v[188:191], v[100:103]
	v_mfma_f32_16x16x32_bf16 v[96:99], v[172:175], v[188:191], v[96:99]
	v_mfma_f32_16x16x32_bf16 v[80:83], v[164:167], v[196:199], v[80:83]
	v_mfma_f32_16x16x32_bf16 v[76:79], v[172:175], v[196:199], v[76:79]
	v_mfma_f32_16x16x32_bf16 v[68:71], v[164:167], v[204:207], v[68:71]
	v_mfma_f32_16x16x32_bf16 v[64:67], v[172:175], v[204:207], v[64:67]
	s_setprio 0
	s_barrier
	s_add_u32 s24, s22, 0x8000
	s_addc_u32 s25, s23, 0
	s_add_i32 s49, s49, s3
	s_mov_b32 m0, s49
	s_nop 0
	ds_read_b128 v[176:179], v147 offset:49152
	ds_read_b128 v[180:183], v147 offset:50176
	ds_read_b128 v[184:187], v147 offset:51200
	ds_read_b128 v[188:191], v147 offset:52224
	ds_read_b128 v[192:195], v147 offset:53248
	ds_read_b128 v[196:199], v147 offset:54272
	ds_read_b128 v[200:203], v147 offset:55296
	ds_read_b128 v[204:207], v147 offset:56320
	global_load_lds_dwordx4 v128, s[24:25]
	s_add_i32 m0, s49, 0x2000
	s_add_u32 s22, s22, 0xc000
	s_addc_u32 s23, s23, 0
	global_load_lds_dwordx4 v130, s[24:25]
	s_add_i32 s24, s50, s3
	s_mov_b32 m0, s24
	s_nop 0
	global_load_lds_dwordx4 v128, s[22:23]
	s_add_i32 m0, s24, 0x2000
	s_nop 0
	global_load_lds_dwordx4 v130, s[22:23]
	s_mov_b32 m0, s36
	s_nop 0
	global_load_lds_dwordx4 v128, s[20:21]
	s_mov_b32 m0, s37
	s_nop 0
	global_load_lds_dwordx4 v130, s[20:21]
	s_waitcnt vmcnt(8)
	s_waitcnt lgkmcnt(0)
	s_barrier
	s_setprio 1
	s_waitcnt lgkmcnt(0)
	v_mfma_f32_16x16x32_bf16 v[60:63], v[138:141], v[176:179], v[60:63]
	v_mfma_f32_16x16x32_bf16 v[56:59], v[152:155], v[176:179], v[56:59]
	v_mfma_f32_16x16x32_bf16 v[48:51], v[138:141], v[184:187], v[48:51]
	v_mfma_f32_16x16x32_bf16 v[40:43], v[152:155], v[184:187], v[40:43]
	v_mfma_f32_16x16x32_bf16 v[28:31], v[138:141], v[192:195], v[28:31]
	v_mfma_f32_16x16x32_bf16 v[24:27], v[152:155], v[192:195], v[24:27]
	v_mfma_f32_16x16x32_bf16 v[16:19], v[138:141], v[200:203], v[16:19]
	v_mfma_f32_16x16x32_bf16 v[8:11], v[152:155], v[200:203], v[8:11]
	v_mfma_f32_16x16x32_bf16 v[60:63], v[148:151], v[180:183], v[60:63]
	v_mfma_f32_16x16x32_bf16 v[56:59], v[156:159], v[180:183], v[56:59]
	v_mfma_f32_16x16x32_bf16 v[48:51], v[148:151], v[188:191], v[48:51]
	v_mfma_f32_16x16x32_bf16 v[40:43], v[156:159], v[188:191], v[40:43]
	v_mfma_f32_16x16x32_bf16 v[28:31], v[148:151], v[196:199], v[28:31]
	v_mfma_f32_16x16x32_bf16 v[24:27], v[156:159], v[196:199], v[24:27]
	v_mfma_f32_16x16x32_bf16 v[16:19], v[148:151], v[204:207], v[16:19]
	v_mfma_f32_16x16x32_bf16 v[8:11], v[156:159], v[204:207], v[8:11]
	s_setprio 0
	s_setprio 1
	v_mfma_f32_16x16x32_bf16 v[52:55], v[160:163], v[176:179], v[52:55]
	v_mfma_f32_16x16x32_bf16 v[44:47], v[168:171], v[176:179], v[44:47]
	v_mfma_f32_16x16x32_bf16 v[36:39], v[160:163], v[184:187], v[36:39]
	v_mfma_f32_16x16x32_bf16 v[32:35], v[168:171], v[184:187], v[32:35]
	v_mfma_f32_16x16x32_bf16 v[20:23], v[160:163], v[192:195], v[20:23]
	v_mfma_f32_16x16x32_bf16 v[12:15], v[168:171], v[192:195], v[12:15]
	v_mfma_f32_16x16x32_bf16 v[4:7], v[160:163], v[200:203], v[4:7]
	v_mfma_f32_16x16x32_bf16 v[0:3], v[168:171], v[200:203], v[0:3]
	v_mfma_f32_16x16x32_bf16 v[52:55], v[164:167], v[180:183], v[52:55]
	v_mfma_f32_16x16x32_bf16 v[44:47], v[172:175], v[180:183], v[44:47]
	v_mfma_f32_16x16x32_bf16 v[36:39], v[164:167], v[188:191], v[36:39]
	v_mfma_f32_16x16x32_bf16 v[32:35], v[172:175], v[188:191], v[32:35]
	v_mfma_f32_16x16x32_bf16 v[20:23], v[164:167], v[196:199], v[20:23]
	v_mfma_f32_16x16x32_bf16 v[12:15], v[172:175], v[196:199], v[12:15]
	v_mfma_f32_16x16x32_bf16 v[4:7], v[164:167], v[204:207], v[4:7]
	v_mfma_f32_16x16x32_bf16 v[0:3], v[172:175], v[204:207], v[0:3]
	s_setprio 0
	s_barrier
	s_add_i32 s48, s48, 2
	s_add_u32 s18, s18, 0x10000
	s_addc_u32 s19, s19, 0
	s_add_u32 s46, s46, 0x10000
	s_addc_u32 s47, s47, 0
	s_cmp_gt_u32 s48, 61
	s_cbranch_scc0 .LBB0_716
	s_and_b64 vcc, exec, s[6:7]
	s_cbranch_vccz .LBB0_719
	s_barrier
